# v27 + GATE epilogue: second per-row stats load issued together with the first (one L2 round trip less per 8-column block)
# speedup vs baseline: 1.0092x; 1.0034x over previous
; DI unsigned pk(float lo, float hi) { f32x2 v = {lo, hi}; bf2_t b = __builtin_convertvector(v, bf2_t); return __builtin_bit_cast(unsigned, b); }
; DI float bflo(unsigned w) { return __uint_as_float(w << 16); }
; DI float bfhi(unsigned w) { return __uint_as_float(w & 0xffff0000u); }
; DI float sigmoidf_(float x) { return 1.0f / (1.0f + __expf(-x)); }
; DI void gemm_epilogue(const GemmDesc& g, f32x4 (&acc)[2][2][4][2], int brow, int bcol, int wr, int wc, int fr, int fq) {
;     ...
;       const int head = col >> g.dvshift;
; #pragma unroll
;       for (int ai = 0; ai < 2; ++ai)
; #pragma unroll
;         for (int m = 0; m < 4; ++m) {
;           const int row = rowb + ai * HALF + m * 16;
;           float rs;
;           { const float* sp = g.f0 + (size_t)row * 32 + head * 8;
;             const f32x4 s0 = gld<f32x4>(sp); float ssum = (s0[0] + s0[1]) + (s0[2] + s0[3]);
;             if (g.dvshift == 9) { const f32x4 s1 = gld<f32x4>(sp + 4); ssum += (s1[0] + s1[1]) + (s1[2] + s1[3]); }
;             rs = rsqrtf(ssum * (g.dvshift == 9 ? (1.0f / 512.0f) : (1.0f / 256.0f)) + EPS); }
;           bf16_t* op = g.o0 + (size_t)row * N + col;
;           const u32x4 ow = gld<u32x4>(op);
;           const float ru = gld<float>(g.rowscale + row);
;           const f32x4 v0 = acc[ai][bj][m][0] * ru, v1 = acc[ai][bj][m][1] * ru;
;           float o[8] = {bflo(ow.x), bfhi(ow.x), bflo(ow.y), bfhi(ow.y), bflo(ow.z), bfhi(ow.z), bflo(ow.w), bfhi(ow.w)};
; #pragma unroll
;           for (int j = 0; j < 4; ++j) { o[j] = o[j] * rs * g0[j] * v0[j] * sigmoidf_(v0[j]); o[4 + j] = o[4 + j] * rs * g1[j] * v1[j] * sigmoidf_(v1[j]); }
;           u32x4 w; w.x = pk(o[0], o[1]); w.y = pk(o[2], o[3]); w.z = pk(o[4], o[5]); w.w = pk(o[6], o[7]);
;           gst<u32x4>(op, w);
.LBB0_219:
	v_readlane_b32 s26, v255, 29
	v_ashrrev_i32_e32 v167, 31, v166
	v_readlane_b32 vcc_lo, v255, 27
	v_ashrrev_i32_e32 v136, s26, v164
	v_lshlrev_b32_e32 v180, 3, v136
	v_lshlrev_b64 v[136:137], 7, v[166:167]
	v_ashrrev_i32_e32 v181, 31, v180
	v_lshl_add_u64 v[182:183], s[66:67], 0, v[136:137]
	v_lshl_add_u64 v[136:137], v[180:181], 2, v[182:183]
	global_load_dwordx4 v[138:141], v[136:137], off
	global_load_dwordx4 v[232:235], v[136:137], off offset:16
	v_readlane_b32 vcc_hi, v255, 28
	s_mov_b32 s26, 0x3b800000
	s_mov_b32 s27, 0x3b800000
	v_cndmask_b32_e64 v142, 0, 1, vcc
	v_cmp_ne_u32_e64 s[44:45], 1, v142
	s_andn2_b64 vcc, exec, vcc
	s_waitcnt vmcnt(0)
	v_mov_b32_e32 v142, v139
	v_mov_b32_e32 v143, v140
	v_mov_b32_e32 v139, v141
	v_pk_add_f32 v[138:139], v[142:143], v[138:139]
	s_nop 0
	v_pk_add_f32 v[138:139], v[138:139], v[138:139] op_sel:[0,1] op_sel_hi:[1,0]
	s_cbranch_vccnz .LBB0_221
	v_mov_b64_e32 v[140:141], v[232:233]
	v_mov_b64_e32 v[142:143], v[234:235]
	s_mov_b32 s27, 0x3b000000
	v_mov_b32_e32 v136, v141
	v_mov_b32_e32 v137, v142
	v_mov_b32_e32 v141, v143
	v_pk_add_f32 v[136:137], v[136:137], v[140:141]
	s_nop 0
	v_add_f32_e32 v136, v136, v137
	v_add_f32_e32 v138, v138, v136
.LBB0_221:
	v_fma_f32 v136, s27, v138, v204
	v_cmp_gt_f32_e32 vcc, s33, v136
	v_mul_f32_e32 v137, 0x4b800000, v136
	v_ashrrev_i32_e32 v165, 31, v164
	v_cndmask_b32_e32 v136, v136, v137, vcc
	v_rsq_f32_e32 v136, v136
	v_lshl_add_u64 v[140:141], v[166:167], 2, s[22:23]
	global_load_dword v168, v[140:141], off
	v_mul_f32_e32 v137, 0x45800000, v136
	v_cndmask_b32_e32 v148, v136, v137, vcc
	v_mad_u64_u32 v[136:137], vcc, v166, s70, 0
	v_mov_b32_e32 v138, v137
	v_mad_u64_u32 v[138:139], vcc, v167, s70, v[138:139]
	v_mov_b32_e32 v137, v138
	v_lshl_add_u64 v[136:137], v[136:137], 1, s[64:65]
	v_lshl_add_u64 v[142:143], v[164:165], 1, v[136:137]
	global_load_dwordx4 v[136:139], v[142:143], off
	s_waitcnt vmcnt(1)
	v_pk_mul_f32 v[172:173], v[124:125], v[168:169] op_sel_hi:[1,0]
	s_waitcnt vmcnt(0)
	v_lshlrev_b32_e32 v170, 16, v136
	v_and_b32_e32 v171, 0xffff0000, v136
	v_mul_f32_e32 v136, 0xbfb8aa3b, v172
	v_exp_f32_e32 v174, v136
	v_mul_f32_e32 v136, 0xbfb8aa3b, v173
	v_exp_f32_e32 v175, v136
	v_pk_mul_f32 v[170:171], v[148:149], v[170:171] op_sel_hi:[0,1]
	v_pk_mul_f32 v[170:171], v[132:133], v[170:171]
	s_nop 0
	v_pk_mul_f32 v[170:171], v[172:173], v[170:171]
	v_pk_add_f32 v[172:173], v[174:175], 1.0 op_sel_hi:[1,0]
	s_nop 0
	v_div_scale_f32 v136, vcc, v173, v173, 1.0
	v_rcp_f32_e32 v167, v136
	s_nop 0
	v_fma_f32 v169, -v136, v167, 1.0
	v_fmac_f32_e32 v167, v169, v167
	v_div_scale_f32 v169, vcc, 1.0, v173, 1.0
	v_mul_f32_e32 v174, v169, v167
	v_fma_f32 v175, -v136, v174, v169
	v_fmac_f32_e32 v174, v175, v167
	v_fma_f32 v136, -v136, v174, v169
	v_div_fmas_f32 v136, v136, v167, v174
	v_div_fixup_f32 v173, v136, v173, 1.0
	v_div_scale_f32 v136, vcc, v172, v172, 1.0
	v_rcp_f32_e32 v167, v136
	s_nop 0
	v_fma_f32 v169, -v136, v167, 1.0
	v_fmac_f32_e32 v167, v169, v167
	v_div_scale_f32 v169, vcc, 1.0, v172, 1.0
	v_mul_f32_e32 v174, v169, v167
	v_fma_f32 v175, -v136, v174, v169
	v_fmac_f32_e32 v174, v175, v167
	v_fma_f32 v136, -v136, v174, v169
	v_div_fmas_f32 v136, v136, v167, v174
	v_pk_mul_f32 v[174:175], v[120:121], v[168:169] op_sel_hi:[1,0]
	v_div_fixup_f32 v172, v136, v172, 1.0
	v_mul_f32_e32 v136, 0xbfb8aa3b, v174
	v_exp_f32_e32 v176, v136
	v_mul_f32_e32 v136, 0xbfb8aa3b, v175
	v_exp_f32_e32 v177, v136
	v_pk_mul_f32 v[170:171], v[172:173], v[170:171]
	v_lshlrev_b32_e32 v172, 16, v138
	v_and_b32_e32 v173, 0xffff0000, v138
	v_pk_mul_f32 v[172:173], v[148:149], v[172:173] op_sel_hi:[0,1]
	v_pk_mul_f32 v[172:173], v[128:129], v[172:173]
	s_nop 0
	v_pk_mul_f32 v[172:173], v[174:175], v[172:173]
	v_pk_add_f32 v[174:175], v[176:177], 1.0 op_sel_hi:[1,0]
	s_nop 0
	v_div_scale_f32 v136, vcc, v175, v175, 1.0
	v_rcp_f32_e32 v138, v136
	s_nop 0
	v_fma_f32 v167, -v136, v138, 1.0
	v_fmac_f32_e32 v138, v167, v138
	v_div_scale_f32 v167, vcc, 1.0, v175, 1.0
	v_mul_f32_e32 v169, v167, v138
	v_fma_f32 v176, -v136, v169, v167
	v_fmac_f32_e32 v169, v176, v138
	v_fma_f32 v136, -v136, v169, v167
	v_div_fmas_f32 v136, v136, v138, v169
	v_div_fixup_f32 v175, v136, v175, 1.0
	v_div_scale_f32 v136, vcc, v174, v174, 1.0
	v_rcp_f32_e32 v138, v136
	s_nop 0
	v_fma_f32 v167, -v136, v138, 1.0
	v_fmac_f32_e32 v138, v167, v138
	v_div_scale_f32 v167, vcc, 1.0, v174, 1.0
	v_mul_f32_e32 v169, v167, v138
	v_fma_f32 v176, -v136, v169, v167
	v_fmac_f32_e32 v169, v176, v138
	v_fma_f32 v136, -v136, v169, v167
	v_div_fmas_f32 v136, v136, v138, v169
	v_pk_mul_f32 v[176:177], v[126:127], v[168:169] op_sel_hi:[1,0]
	v_div_fixup_f32 v174, v136, v174, 1.0
	v_mul_f32_e32 v138, 0xbfb8aa3b, v176
	v_pk_mul_f32 v[172:173], v[174:175], v[172:173]
	v_exp_f32_e32 v174, v138
	v_mul_f32_e32 v138, 0xbfb8aa3b, v177
	v_exp_f32_e32 v175, v138
	v_lshlrev_b32_e32 v136, 16, v137
	v_and_b32_e32 v137, 0xffff0000, v137
	v_pk_mul_f32 v[136:137], v[148:149], v[136:137] op_sel_hi:[0,1]
	v_pk_add_f32 v[174:175], v[174:175], 1.0 op_sel_hi:[1,0]
	v_pk_mul_f32 v[136:137], v[134:135], v[136:137]
	v_div_scale_f32 v138, vcc, v175, v175, 1.0
	v_rcp_f32_e32 v167, v138
	v_pk_mul_f32 v[136:137], v[176:177], v[136:137]
	v_fma_f32 v169, -v138, v167, 1.0
	v_fmac_f32_e32 v167, v169, v167
	v_div_scale_f32 v169, vcc, 1.0, v175, 1.0
	v_mul_f32_e32 v176, v169, v167
	v_fma_f32 v177, -v138, v176, v169
	v_fmac_f32_e32 v176, v177, v167
	v_fma_f32 v138, -v138, v176, v169
	v_div_fmas_f32 v138, v138, v167, v176
	v_div_fixup_f32 v175, v138, v175, 1.0
	v_div_scale_f32 v138, vcc, v174, v174, 1.0
	v_rcp_f32_e32 v167, v138
	s_nop 0
	v_fma_f32 v169, -v138, v167, 1.0
; DI unsigned pk(float lo, float hi) { f32x2 v = {lo, hi}; bf2_t b = __builtin_convertvector(v, bf2_t); return __builtin_bit_cast(unsigned, b); }
; DI float bflo(unsigned w) { return __uint_as_float(w << 16); }
; DI float bfhi(unsigned w) { return __uint_as_float(w & 0xffff0000u); }
; DI float sigmoidf_(float x) { return 1.0f / (1.0f + __expf(-x)); }
; DI void gemm_epilogue(const GemmDesc& g, f32x4 (&acc)[2][2][4][2], int brow, int bcol, int wr, int wc, int fr, int fq) {
;     ...
;           const int row = rowb + ai * HALF + m * 16;
;           float rs;
;           { const float* sp = g.f0 + (size_t)row * 32 + head * 8;
;             const f32x4 s0 = gld<f32x4>(sp); float ssum = (s0[0] + s0[1]) + (s0[2] + s0[3]);
;             if (g.dvshift == 9) { const f32x4 s1 = gld<f32x4>(sp + 4); ssum += (s1[0] + s1[1]) + (s1[2] + s1[3]); }
;             rs = rsqrtf(ssum * (g.dvshift == 9 ? (1.0f / 512.0f) : (1.0f / 256.0f)) + EPS); }
;           bf16_t* op = g.o0 + (size_t)row * N + col;
;           const u32x4 ow = gld<u32x4>(op);
;           const float ru = gld<float>(g.rowscale + row);
;           const f32x4 v0 = acc[ai][bj][m][0] * ru, v1 = acc[ai][bj][m][1] * ru;
;           float o[8] = {bflo(ow.x), bfhi(ow.x), bflo(ow.y), bfhi(ow.y), bflo(ow.z), bfhi(ow.z), bflo(ow.w), bfhi(ow.w)};
; #pragma unroll
;           for (int j = 0; j < 4; ++j) { o[j] = o[j] * rs * g0[j] * v0[j] * sigmoidf_(v0[j]); o[4 + j] = o[4 + j] * rs * g1[j] * v1[j] * sigmoidf_(v1[j]); }
;           u32x4 w; w.x = pk(o[0], o[1]); w.y = pk(o[2], o[3]); w.z = pk(o[4], o[5]); w.w = pk(o[6], o[7]);
;           gst<u32x4>(op, w);
	v_fmac_f32_e32 v167, v169, v167
	v_div_scale_f32 v169, vcc, 1.0, v174, 1.0
	v_mul_f32_e32 v176, v169, v167
	v_fma_f32 v177, -v138, v176, v169
	v_fmac_f32_e32 v176, v177, v167
	v_fma_f32 v138, -v138, v176, v169
	v_div_fmas_f32 v138, v138, v167, v176
	v_div_fixup_f32 v174, v138, v174, 1.0
	v_pk_mul_f32 v[174:175], v[174:175], v[136:137]
	v_lshlrev_b32_e32 v136, 16, v139
	v_and_b32_e32 v137, 0xffff0000, v139
	v_pk_mul_f32 v[136:137], v[148:149], v[136:137] op_sel_hi:[0,1]
	v_pk_mul_f32 v[138:139], v[122:123], v[168:169] op_sel_hi:[1,0]
	v_pk_mul_f32 v[136:137], v[130:131], v[136:137]
	v_mul_f32_e32 v167, 0xbfb8aa3b, v138
	v_pk_mul_f32 v[136:137], v[138:139], v[136:137]
	v_mul_f32_e32 v138, 0xbfb8aa3b, v139
	v_exp_f32_e32 v168, v167
	v_exp_f32_e32 v169, v138
	s_nop 0
	v_pk_add_f32 v[138:139], v[168:169], 1.0 op_sel_hi:[1,0]
	s_nop 0
	v_div_scale_f32 v148, vcc, v139, v139, 1.0
	v_rcp_f32_e32 v167, v148
	s_nop 0
	v_fma_f32 v168, -v148, v167, 1.0
	v_fmac_f32_e32 v167, v168, v167
	v_div_scale_f32 v168, vcc, 1.0, v139, 1.0
	v_mul_f32_e32 v169, v168, v167
	v_fma_f32 v176, -v148, v169, v168
	v_fmac_f32_e32 v169, v176, v167
	v_fma_f32 v148, -v148, v169, v168
	v_div_fmas_f32 v148, v148, v167, v169
	v_div_fixup_f32 v139, v148, v139, 1.0
	v_div_scale_f32 v148, vcc, v138, v138, 1.0
	v_rcp_f32_e32 v167, v148
	s_nop 0
	v_fma_f32 v168, -v148, v167, 1.0
	v_fmac_f32_e32 v167, v168, v167
	v_div_scale_f32 v168, vcc, 1.0, v138, 1.0
	v_mul_f32_e32 v169, v168, v167
	v_fma_f32 v176, -v148, v169, v168
	v_fmac_f32_e32 v169, v176, v167
	v_fma_f32 v148, -v148, v169, v168
	v_div_fmas_f32 v148, v148, v167, v169
	v_div_fixup_f32 v138, v148, v138, 1.0
	v_pk_mul_f32 v[168:169], v[138:139], v[136:137]
	v_cvt_pk_bf16_f32 v136, v170, v171
	v_cvt_pk_bf16_f32 v137, v174, v175
	v_cvt_pk_bf16_f32 v138, v172, v173
	v_cvt_pk_bf16_f32 v139, v168, v169
	global_store_dwordx4 v[142:143], v[136:139], off
	s_and_b64 vcc, exec, s[44:45]
	s_nop 0
	v_or_b32_e32 v136, 16, v166
	v_ashrrev_i32_e32 v137, 31, v136
	v_lshlrev_b64 v[138:139], 7, v[136:137]
	v_lshl_add_u64 v[184:185], s[66:67], 0, v[138:139]
	v_lshl_add_u64 v[168:169], v[180:181], 2, v[184:185]
	global_load_dwordx4 v[170:173], v[168:169], off
	global_load_dwordx4 v[232:235], v[168:169], off offset:16
	s_waitcnt vmcnt(0)
	v_mov_b32_e32 v138, v171
	v_mov_b32_e32 v139, v172
	v_mov_b32_e32 v171, v173
	v_pk_add_f32 v[138:139], v[138:139], v[170:171]
	s_nop 0
	v_pk_add_f32 v[138:139], v[138:139], v[138:139] op_sel:[0,1] op_sel_hi:[1,0]
	s_cbranch_vccnz .LBB0_223
	v_mov_b64_e32 v[168:169], v[232:233]
	v_mov_b64_e32 v[170:171], v[234:235]
	s_mov_b32 s26, 0x3b000000
	v_mov_b32_e32 v172, v169
	v_mov_b32_e32 v173, v170
	v_mov_b32_e32 v169, v171
	v_pk_add_f32 v[168:169], v[172:173], v[168:169]
	s_nop 0
	v_add_f32_e32 v139, v168, v169
	v_add_f32_e32 v138, v138, v139
.LBB0_223:
	v_fma_f32 v138, s26, v138, v204
	v_cmp_gt_f32_e32 vcc, s33, v138
	v_mul_f32_e32 v139, 0x4b800000, v138
	s_nop 0
	v_cndmask_b32_e32 v138, v138, v139, vcc
	v_rsq_f32_e32 v138, v138
	s_nop 0
	v_mul_f32_e32 v139, 0x45800000, v138
	v_cndmask_b32_e32 v148, v138, v139, vcc
	v_mad_u64_u32 v[138:139], s[26:27], v136, s70, 0
	v_mov_b32_e32 v136, v139
	v_mad_u64_u32 v[136:137], s[26:27], v137, s70, v[136:137]
	v_mov_b32_e32 v139, v136
	v_lshl_add_u64 v[136:137], v[138:139], 1, s[64:65]
	v_lshl_add_u64 v[168:169], v[164:165], 1, v[136:137]
	global_load_dwordx4 v[136:139], v[168:169], off
	global_load_dword v170, v[140:141], off offset:64
	s_waitcnt vmcnt(1)
	v_lshlrev_b32_e32 v172, 16, v136
	s_waitcnt vmcnt(0)
	v_pk_mul_f32 v[174:175], v[116:117], v[170:171] op_sel_hi:[1,0]
	v_and_b32_e32 v173, 0xffff0000, v136
	v_mul_f32_e32 v136, 0xbfb8aa3b, v174
	v_exp_f32_e32 v176, v136
	v_mul_f32_e32 v136, 0xbfb8aa3b, v175
	v_exp_f32_e32 v177, v136
	v_pk_mul_f32 v[172:173], v[148:149], v[172:173] op_sel_hi:[0,1]
	v_pk_mul_f32 v[172:173], v[132:133], v[172:173]
	s_nop 0
	v_pk_mul_f32 v[172:173], v[174:175], v[172:173]
	v_pk_add_f32 v[174:175], v[176:177], 1.0 op_sel_hi:[1,0]
	s_nop 0
	v_div_scale_f32 v136, s[26:27], v175, v175, 1.0
	v_rcp_f32_e32 v167, v136
	s_nop 0
	v_fma_f32 v171, -v136, v167, 1.0
	v_fmac_f32_e32 v167, v171, v167
	v_div_scale_f32 v171, vcc, 1.0, v175, 1.0
	v_mul_f32_e32 v176, v171, v167
	v_fma_f32 v177, -v136, v176, v171
	v_fmac_f32_e32 v176, v177, v167
	v_fma_f32 v136, -v136, v176, v171
	v_div_fmas_f32 v136, v136, v167, v176
	v_div_fixup_f32 v175, v136, v175, 1.0
	v_div_scale_f32 v136, s[26:27], v174, v174, 1.0
	v_rcp_f32_e32 v167, v136
	s_nop 0
	v_fma_f32 v171, -v136, v167, 1.0
	v_fmac_f32_e32 v167, v171, v167
	v_div_scale_f32 v171, vcc, 1.0, v174, 1.0
	v_mul_f32_e32 v176, v171, v167
	v_fma_f32 v177, -v136, v176, v171
	v_fmac_f32_e32 v176, v177, v167
	v_fma_f32 v136, -v136, v176, v171
	v_div_fmas_f32 v136, v136, v167, v176
	v_pk_mul_f32 v[176:177], v[112:113], v[170:171] op_sel_hi:[1,0]
	v_div_fixup_f32 v174, v136, v174, 1.0
	v_mul_f32_e32 v136, 0xbfb8aa3b, v176
	v_exp_f32_e32 v178, v136
	v_mul_f32_e32 v136, 0xbfb8aa3b, v177
	v_exp_f32_e32 v179, v136
	v_pk_mul_f32 v[172:173], v[174:175], v[172:173]
	v_lshlrev_b32_e32 v174, 16, v138
	v_and_b32_e32 v175, 0xffff0000, v138
	v_pk_mul_f32 v[174:175], v[148:149], v[174:175] op_sel_hi:[0,1]
	v_pk_mul_f32 v[174:175], v[128:129], v[174:175]
	s_nop 0
	v_pk_mul_f32 v[174:175], v[176:177], v[174:175]
	v_pk_add_f32 v[176:177], v[178:179], 1.0 op_sel_hi:[1,0]
	s_nop 0
	v_div_scale_f32 v136, s[26:27], v177, v177, 1.0
	v_rcp_f32_e32 v138, v136
	s_nop 0
	v_fma_f32 v167, -v136, v138, 1.0
	v_fmac_f32_e32 v138, v167, v138
	v_div_scale_f32 v167, vcc, 1.0, v177, 1.0
	v_mul_f32_e32 v171, v167, v138
	v_fma_f32 v178, -v136, v171, v167
; DI unsigned pk(float lo, float hi) { f32x2 v = {lo, hi}; bf2_t b = __builtin_convertvector(v, bf2_t); return __builtin_bit_cast(unsigned, b); }
; DI float bflo(unsigned w) { return __uint_as_float(w << 16); }
; DI float bfhi(unsigned w) { return __uint_as_float(w & 0xffff0000u); }
; DI float sigmoidf_(float x) { return 1.0f / (1.0f + __expf(-x)); }
; DI void gemm_epilogue(const GemmDesc& g, f32x4 (&acc)[2][2][4][2], int brow, int bcol, int wr, int wc, int fr, int fq) {
;     ...
;           const int row = rowb + ai * HALF + m * 16;
;           float rs;
;           { const float* sp = g.f0 + (size_t)row * 32 + head * 8;
;             const f32x4 s0 = gld<f32x4>(sp); float ssum = (s0[0] + s0[1]) + (s0[2] + s0[3]);
;             if (g.dvshift == 9) { const f32x4 s1 = gld<f32x4>(sp + 4); ssum += (s1[0] + s1[1]) + (s1[2] + s1[3]); }
;             rs = rsqrtf(ssum * (g.dvshift == 9 ? (1.0f / 512.0f) : (1.0f / 256.0f)) + EPS); }
;           bf16_t* op = g.o0 + (size_t)row * N + col;
;           const u32x4 ow = gld<u32x4>(op);
;           const float ru = gld<float>(g.rowscale + row);
;           const f32x4 v0 = acc[ai][bj][m][0] * ru, v1 = acc[ai][bj][m][1] * ru;
;           float o[8] = {bflo(ow.x), bfhi(ow.x), bflo(ow.y), bfhi(ow.y), bflo(ow.z), bfhi(ow.z), bflo(ow.w), bfhi(ow.w)};
; #pragma unroll
;           for (int j = 0; j < 4; ++j) { o[j] = o[j] * rs * g0[j] * v0[j] * sigmoidf_(v0[j]); o[4 + j] = o[4 + j] * rs * g1[j] * v1[j] * sigmoidf_(v1[j]); }
;           u32x4 w; w.x = pk(o[0], o[1]); w.y = pk(o[2], o[3]); w.z = pk(o[4], o[5]); w.w = pk(o[6], o[7]);
;           gst<u32x4>(op, w);
	v_fmac_f32_e32 v171, v178, v138
	v_fma_f32 v136, -v136, v171, v167
	v_div_fmas_f32 v136, v136, v138, v171
	v_div_fixup_f32 v177, v136, v177, 1.0
	v_div_scale_f32 v136, s[26:27], v176, v176, 1.0
	v_rcp_f32_e32 v138, v136
	s_nop 0
	v_fma_f32 v167, -v136, v138, 1.0
	v_fmac_f32_e32 v138, v167, v138
	v_div_scale_f32 v167, vcc, 1.0, v176, 1.0
	v_mul_f32_e32 v171, v167, v138
	v_fma_f32 v178, -v136, v171, v167
	v_fmac_f32_e32 v171, v178, v138
	v_fma_f32 v136, -v136, v171, v167
	v_div_fmas_f32 v136, v136, v138, v171
	v_pk_mul_f32 v[178:179], v[118:119], v[170:171] op_sel_hi:[1,0]
	v_div_fixup_f32 v176, v136, v176, 1.0
	v_mul_f32_e32 v138, 0xbfb8aa3b, v178
	v_pk_mul_f32 v[174:175], v[176:177], v[174:175]
	v_exp_f32_e32 v176, v138
	v_mul_f32_e32 v138, 0xbfb8aa3b, v179
	v_exp_f32_e32 v177, v138
	v_lshlrev_b32_e32 v136, 16, v137
	v_and_b32_e32 v137, 0xffff0000, v137
	v_pk_mul_f32 v[136:137], v[148:149], v[136:137] op_sel_hi:[0,1]
	v_pk_add_f32 v[176:177], v[176:177], 1.0 op_sel_hi:[1,0]
	v_pk_mul_f32 v[136:137], v[134:135], v[136:137]
	v_div_scale_f32 v138, s[26:27], v177, v177, 1.0
	v_rcp_f32_e32 v167, v138
	v_pk_mul_f32 v[136:137], v[178:179], v[136:137]
	v_fma_f32 v171, -v138, v167, 1.0
	v_fmac_f32_e32 v167, v171, v167
	v_div_scale_f32 v171, vcc, 1.0, v177, 1.0
	v_mul_f32_e32 v178, v171, v167
	v_fma_f32 v179, -v138, v178, v171
	v_fmac_f32_e32 v178, v179, v167
	v_fma_f32 v138, -v138, v178, v171
	v_div_fmas_f32 v138, v138, v167, v178
	v_div_fixup_f32 v177, v138, v177, 1.0
	v_div_scale_f32 v138, s[26:27], v176, v176, 1.0
	v_rcp_f32_e32 v167, v138
	s_nop 0
	v_fma_f32 v171, -v138, v167, 1.0
	v_fmac_f32_e32 v167, v171, v167
	v_div_scale_f32 v171, vcc, 1.0, v176, 1.0
	v_mul_f32_e32 v178, v171, v167
	v_fma_f32 v179, -v138, v178, v171
	v_fmac_f32_e32 v178, v179, v167
	v_fma_f32 v138, -v138, v178, v171
	v_div_fmas_f32 v138, v138, v167, v178
	v_div_fixup_f32 v176, v138, v176, 1.0
	v_pk_mul_f32 v[176:177], v[176:177], v[136:137]
	v_lshlrev_b32_e32 v136, 16, v139
	v_and_b32_e32 v137, 0xffff0000, v139
	v_pk_mul_f32 v[136:137], v[148:149], v[136:137] op_sel_hi:[0,1]
	v_pk_mul_f32 v[138:139], v[114:115], v[170:171] op_sel_hi:[1,0]
	v_pk_mul_f32 v[136:137], v[130:131], v[136:137]
	v_mul_f32_e32 v167, 0xbfb8aa3b, v138
	v_pk_mul_f32 v[136:137], v[138:139], v[136:137]
	v_mul_f32_e32 v138, 0xbfb8aa3b, v139
	v_exp_f32_e32 v170, v167
	v_exp_f32_e32 v171, v138
	s_nop 0
	v_pk_add_f32 v[138:139], v[170:171], 1.0 op_sel_hi:[1,0]
	s_nop 0
	v_div_scale_f32 v148, s[26:27], v139, v139, 1.0
	v_rcp_f32_e32 v167, v148
	s_nop 0
	v_fma_f32 v170, -v148, v167, 1.0
	v_fmac_f32_e32 v167, v170, v167
	v_div_scale_f32 v170, vcc, 1.0, v139, 1.0
	v_mul_f32_e32 v171, v170, v167
	v_fma_f32 v178, -v148, v171, v170
	v_fmac_f32_e32 v171, v178, v167
	v_fma_f32 v148, -v148, v171, v170
	v_div_fmas_f32 v148, v148, v167, v171
	v_div_fixup_f32 v139, v148, v139, 1.0
	v_div_scale_f32 v148, s[26:27], v138, v138, 1.0
	v_rcp_f32_e32 v167, v148
	s_mov_b32 s26, 0x3b800000
	s_mov_b32 s27, 0x3b800000
	v_fma_f32 v170, -v148, v167, 1.0
	v_fmac_f32_e32 v167, v170, v167
	v_div_scale_f32 v170, vcc, 1.0, v138, 1.0
	v_mul_f32_e32 v171, v170, v167
	v_fma_f32 v178, -v148, v171, v170
	v_fmac_f32_e32 v171, v178, v167
	v_fma_f32 v148, -v148, v171, v170
	v_div_fmas_f32 v148, v148, v167, v171
	v_div_fixup_f32 v138, v148, v138, 1.0
	v_pk_mul_f32 v[170:171], v[138:139], v[136:137]
	v_cvt_pk_bf16_f32 v136, v172, v173
	v_cvt_pk_bf16_f32 v137, v176, v177
	v_cvt_pk_bf16_f32 v138, v174, v175
	v_cvt_pk_bf16_f32 v139, v170, v171
	global_store_dwordx4 v[168:169], v[136:139], off
	s_and_b64 vcc, exec, s[44:45]
	s_nop 0
	v_or_b32_e32 v136, 32, v166
	v_ashrrev_i32_e32 v137, 31, v136
	v_lshlrev_b64 v[138:139], 7, v[136:137]
	v_lshl_add_u64 v[186:187], s[66:67], 0, v[138:139]
	v_lshl_add_u64 v[170:171], v[180:181], 2, v[186:187]
	global_load_dwordx4 v[172:175], v[170:171], off
	global_load_dwordx4 v[232:235], v[170:171], off offset:16
	s_waitcnt vmcnt(0)
	v_mov_b32_e32 v138, v173
	v_mov_b32_e32 v139, v174
	v_mov_b32_e32 v173, v175
	v_pk_add_f32 v[138:139], v[138:139], v[172:173]
	s_nop 0
	v_pk_add_f32 v[138:139], v[138:139], v[138:139] op_sel:[0,1] op_sel_hi:[1,0]
	s_cbranch_vccnz .LBB0_225
	v_mov_b64_e32 v[170:171], v[232:233]
	v_mov_b64_e32 v[172:173], v[234:235]
	s_mov_b32 s27, 0x3b000000
	v_mov_b32_e32 v174, v171
	v_mov_b32_e32 v175, v172
	v_mov_b32_e32 v171, v173
	v_pk_add_f32 v[170:171], v[174:175], v[170:171]
	s_nop 0
	v_add_f32_e32 v139, v170, v171
	v_add_f32_e32 v138, v138, v139
; DI unsigned pk(float lo, float hi) { f32x2 v = {lo, hi}; bf2_t b = __builtin_convertvector(v, bf2_t); return __builtin_bit_cast(unsigned, b); }
; DI float bflo(unsigned w) { return __uint_as_float(w << 16); }
; DI float bfhi(unsigned w) { return __uint_as_float(w & 0xffff0000u); }
; DI float sigmoidf_(float x) { return 1.0f / (1.0f + __expf(-x)); }
; DI void gemm_epilogue(const GemmDesc& g, f32x4 (&acc)[2][2][4][2], int brow, int bcol, int wr, int wc, int fr, int fq) {
;     ...
;           const int row = rowb + ai * HALF + m * 16;
;           float rs;
;           { const float* sp = g.f0 + (size_t)row * 32 + head * 8;
;             const f32x4 s0 = gld<f32x4>(sp); float ssum = (s0[0] + s0[1]) + (s0[2] + s0[3]);
;             if (g.dvshift == 9) { const f32x4 s1 = gld<f32x4>(sp + 4); ssum += (s1[0] + s1[1]) + (s1[2] + s1[3]); }
;             rs = rsqrtf(ssum * (g.dvshift == 9 ? (1.0f / 512.0f) : (1.0f / 256.0f)) + EPS); }
;           bf16_t* op = g.o0 + (size_t)row * N + col;
;           const u32x4 ow = gld<u32x4>(op);
;           const float ru = gld<float>(g.rowscale + row);
;           const f32x4 v0 = acc[ai][bj][m][0] * ru, v1 = acc[ai][bj][m][1] * ru;
;           float o[8] = {bflo(ow.x), bfhi(ow.x), bflo(ow.y), bfhi(ow.y), bflo(ow.z), bfhi(ow.z), bflo(ow.w), bfhi(ow.w)};
; #pragma unroll
;           for (int j = 0; j < 4; ++j) { o[j] = o[j] * rs * g0[j] * v0[j] * sigmoidf_(v0[j]); o[4 + j] = o[4 + j] * rs * g1[j] * v1[j] * sigmoidf_(v1[j]); }
;           u32x4 w; w.x = pk(o[0], o[1]); w.y = pk(o[2], o[3]); w.z = pk(o[4], o[5]); w.w = pk(o[6], o[7]);
;           gst<u32x4>(op, w);
.LBB0_225:
	v_fma_f32 v138, s27, v138, v204
	v_cmp_gt_f32_e32 vcc, s33, v138
	v_mul_f32_e32 v139, 0x4b800000, v138
	s_nop 0
	v_cndmask_b32_e32 v138, v138, v139, vcc
	v_rsq_f32_e32 v138, v138
	s_nop 0
	v_mul_f32_e32 v139, 0x45800000, v138
	v_cndmask_b32_e32 v148, v138, v139, vcc
	v_mad_u64_u32 v[138:139], vcc, v136, s70, 0
	v_mov_b32_e32 v136, v139
	v_mad_u64_u32 v[136:137], vcc, v137, s70, v[136:137]
	v_mov_b32_e32 v139, v136
	v_lshl_add_u64 v[136:137], v[138:139], 1, s[64:65]
	v_lshl_add_u64 v[170:171], v[164:165], 1, v[136:137]
	global_load_dwordx4 v[136:139], v[170:171], off
	global_load_dword v172, v[140:141], off offset:128
	s_waitcnt vmcnt(1)
	v_lshlrev_b32_e32 v174, 16, v136
	s_waitcnt vmcnt(0)
	v_pk_mul_f32 v[176:177], v[108:109], v[172:173] op_sel_hi:[1,0]
	v_and_b32_e32 v175, 0xffff0000, v136
	v_mul_f32_e32 v136, 0xbfb8aa3b, v176
	v_exp_f32_e32 v178, v136
	v_mul_f32_e32 v136, 0xbfb8aa3b, v177
	v_exp_f32_e32 v179, v136
	v_pk_mul_f32 v[174:175], v[148:149], v[174:175] op_sel_hi:[0,1]
	v_pk_mul_f32 v[174:175], v[132:133], v[174:175]
	s_nop 0
	v_pk_mul_f32 v[174:175], v[176:177], v[174:175]
	v_pk_add_f32 v[176:177], v[178:179], 1.0 op_sel_hi:[1,0]
	s_nop 0
	v_div_scale_f32 v136, vcc, v177, v177, 1.0
	v_rcp_f32_e32 v167, v136
	s_nop 0
	v_fma_f32 v173, -v136, v167, 1.0
	v_fmac_f32_e32 v167, v173, v167
	v_div_scale_f32 v173, vcc, 1.0, v177, 1.0
	v_mul_f32_e32 v178, v173, v167
	v_fma_f32 v179, -v136, v178, v173
	v_fmac_f32_e32 v178, v179, v167
	v_fma_f32 v136, -v136, v178, v173
	v_div_fmas_f32 v136, v136, v167, v178
	v_div_fixup_f32 v177, v136, v177, 1.0
	v_div_scale_f32 v136, vcc, v176, v176, 1.0
	v_rcp_f32_e32 v167, v136
	s_nop 0
	v_fma_f32 v173, -v136, v167, 1.0
	v_fmac_f32_e32 v167, v173, v167
	v_div_scale_f32 v173, vcc, 1.0, v176, 1.0
	v_mul_f32_e32 v178, v173, v167
	v_fma_f32 v179, -v136, v178, v173
	v_fmac_f32_e32 v178, v179, v167
	v_fma_f32 v136, -v136, v178, v173
	v_div_fmas_f32 v136, v136, v167, v178
	v_pk_mul_f32 v[178:179], v[104:105], v[172:173] op_sel_hi:[1,0]
	v_div_fixup_f32 v176, v136, v176, 1.0
	v_mul_f32_e32 v136, 0xbfb8aa3b, v178
	v_exp_f32_e32 v188, v136
	v_mul_f32_e32 v136, 0xbfb8aa3b, v179
	v_exp_f32_e32 v189, v136
	v_pk_mul_f32 v[174:175], v[176:177], v[174:175]
	v_lshlrev_b32_e32 v176, 16, v138
	v_and_b32_e32 v177, 0xffff0000, v138
	v_pk_mul_f32 v[176:177], v[148:149], v[176:177] op_sel_hi:[0,1]
	v_pk_mul_f32 v[176:177], v[128:129], v[176:177]
	s_nop 0
	v_pk_mul_f32 v[176:177], v[178:179], v[176:177]
	v_pk_add_f32 v[178:179], v[188:189], 1.0 op_sel_hi:[1,0]
	s_nop 0
	v_div_scale_f32 v136, vcc, v179, v179, 1.0
	v_rcp_f32_e32 v138, v136
	s_nop 0
	v_fma_f32 v167, -v136, v138, 1.0
	v_fmac_f32_e32 v138, v167, v138
	v_div_scale_f32 v167, vcc, 1.0, v179, 1.0
	v_mul_f32_e32 v173, v167, v138
	v_fma_f32 v188, -v136, v173, v167
	v_fmac_f32_e32 v173, v188, v138
	v_fma_f32 v136, -v136, v173, v167
	v_div_fmas_f32 v136, v136, v138, v173
	v_div_fixup_f32 v179, v136, v179, 1.0
	v_div_scale_f32 v136, vcc, v178, v178, 1.0
	v_rcp_f32_e32 v138, v136
	s_nop 0
	v_fma_f32 v167, -v136, v138, 1.0
	v_fmac_f32_e32 v138, v167, v138
	v_div_scale_f32 v167, vcc, 1.0, v178, 1.0
	v_mul_f32_e32 v173, v167, v138
	v_fma_f32 v188, -v136, v173, v167
	v_fmac_f32_e32 v173, v188, v138
	v_fma_f32 v136, -v136, v173, v167
	v_div_fmas_f32 v136, v136, v138, v173
	v_pk_mul_f32 v[188:189], v[110:111], v[172:173] op_sel_hi:[1,0]
	v_div_fixup_f32 v178, v136, v178, 1.0
	v_mul_f32_e32 v138, 0xbfb8aa3b, v188
	v_pk_mul_f32 v[176:177], v[178:179], v[176:177]
	v_exp_f32_e32 v178, v138
	v_mul_f32_e32 v138, 0xbfb8aa3b, v189
	v_exp_f32_e32 v179, v138
	v_lshlrev_b32_e32 v136, 16, v137
	v_and_b32_e32 v137, 0xffff0000, v137
	v_pk_mul_f32 v[136:137], v[148:149], v[136:137] op_sel_hi:[0,1]
	v_pk_add_f32 v[178:179], v[178:179], 1.0 op_sel_hi:[1,0]
	v_pk_mul_f32 v[136:137], v[134:135], v[136:137]
	v_div_scale_f32 v138, vcc, v179, v179, 1.0
	v_rcp_f32_e32 v167, v138
	v_pk_mul_f32 v[136:137], v[188:189], v[136:137]
	v_fma_f32 v173, -v138, v167, 1.0
	v_fmac_f32_e32 v167, v173, v167
	v_div_scale_f32 v173, vcc, 1.0, v179, 1.0
	v_mul_f32_e32 v188, v173, v167
	v_fma_f32 v189, -v138, v188, v173
	v_fmac_f32_e32 v188, v189, v167
	v_fma_f32 v138, -v138, v188, v173
	v_div_fmas_f32 v138, v138, v167, v188
	v_div_fixup_f32 v179, v138, v179, 1.0
	v_div_scale_f32 v138, vcc, v178, v178, 1.0
	v_rcp_f32_e32 v167, v138
	s_nop 0
	v_fma_f32 v173, -v138, v167, 1.0
	v_fmac_f32_e32 v167, v173, v167
	v_div_scale_f32 v173, vcc, 1.0, v178, 1.0
	v_mul_f32_e32 v188, v173, v167
	v_fma_f32 v189, -v138, v188, v173
	v_fmac_f32_e32 v188, v189, v167
	v_fma_f32 v138, -v138, v188, v173
	v_div_fmas_f32 v138, v138, v167, v188
	v_div_fixup_f32 v178, v138, v178, 1.0
	v_pk_mul_f32 v[178:179], v[178:179], v[136:137]
	v_lshlrev_b32_e32 v136, 16, v139
	v_and_b32_e32 v137, 0xffff0000, v139
	v_pk_mul_f32 v[136:137], v[148:149], v[136:137] op_sel_hi:[0,1]
	v_pk_mul_f32 v[138:139], v[106:107], v[172:173] op_sel_hi:[1,0]
	v_pk_mul_f32 v[136:137], v[130:131], v[136:137]
	v_mul_f32_e32 v167, 0xbfb8aa3b, v138
	v_pk_mul_f32 v[136:137], v[138:139], v[136:137]
	v_mul_f32_e32 v138, 0xbfb8aa3b, v139
	v_exp_f32_e32 v172, v167
	v_exp_f32_e32 v173, v138
	s_nop 0
	v_pk_add_f32 v[138:139], v[172:173], 1.0 op_sel_hi:[1,0]
	s_nop 0
	v_div_scale_f32 v148, vcc, v139, v139, 1.0
	v_rcp_f32_e32 v167, v148
	s_nop 0
	v_fma_f32 v172, -v148, v167, 1.0
	v_fmac_f32_e32 v167, v172, v167
	v_div_scale_f32 v172, vcc, 1.0, v139, 1.0
	v_mul_f32_e32 v173, v172, v167
	v_fma_f32 v188, -v148, v173, v172
	v_fmac_f32_e32 v173, v188, v167
	v_fma_f32 v148, -v148, v173, v172
	v_div_fmas_f32 v148, v148, v167, v173
	v_div_fixup_f32 v139, v148, v139, 1.0
	v_div_scale_f32 v148, vcc, v138, v138, 1.0
	v_rcp_f32_e32 v167, v148
	s_nop 0
	v_fma_f32 v172, -v148, v167, 1.0
	v_fmac_f32_e32 v167, v172, v167
	v_div_scale_f32 v172, vcc, 1.0, v138, 1.0
	v_mul_f32_e32 v173, v172, v167
	v_fma_f32 v188, -v148, v173, v172
	v_fmac_f32_e32 v173, v188, v167
	v_fma_f32 v148, -v148, v173, v172
	v_div_fmas_f32 v148, v148, v167, v173
	v_div_fixup_f32 v138, v148, v138, 1.0
	v_pk_mul_f32 v[172:173], v[138:139], v[136:137]
	v_cvt_pk_bf16_f32 v136, v174, v175
	v_cvt_pk_bf16_f32 v137, v178, v179
	v_cvt_pk_bf16_f32 v138, v176, v177
	v_cvt_pk_bf16_f32 v139, v172, v173
	global_store_dwordx4 v[170:171], v[136:139], off
	s_and_b64 vcc, exec, s[44:45]
	s_nop 0
	v_or_b32_e32 v136, 48, v166
	v_ashrrev_i32_e32 v137, 31, v136
	v_lshlrev_b64 v[138:139], 7, v[136:137]
	v_lshl_add_u64 v[188:189], s[66:67], 0, v[138:139]
	v_lshl_add_u64 v[172:173], v[180:181], 2, v[188:189]
	global_load_dwordx4 v[174:177], v[172:173], off
	global_load_dwordx4 v[232:235], v[172:173], off offset:16
	s_waitcnt vmcnt(0)
	v_mov_b32_e32 v138, v175
	v_mov_b32_e32 v139, v176
	v_mov_b32_e32 v175, v177
	v_pk_add_f32 v[138:139], v[138:139], v[174:175]
	s_nop 0
	v_pk_add_f32 v[138:139], v[138:139], v[138:139] op_sel:[0,1] op_sel_hi:[1,0]
	s_cbranch_vccnz .LBB0_227
; DI unsigned pk(float lo, float hi) { f32x2 v = {lo, hi}; bf2_t b = __builtin_convertvector(v, bf2_t); return __builtin_bit_cast(unsigned, b); }
; DI float bflo(unsigned w) { return __uint_as_float(w << 16); }
; DI float bfhi(unsigned w) { return __uint_as_float(w & 0xffff0000u); }
; DI float sigmoidf_(float x) { return 1.0f / (1.0f + __expf(-x)); }
; DI void gemm_epilogue(const GemmDesc& g, f32x4 (&acc)[2][2][4][2], int brow, int bcol, int wr, int wc, int fr, int fq) {
;     ...
;           const int row = rowb + ai * HALF + m * 16;
;           float rs;
;           { const float* sp = g.f0 + (size_t)row * 32 + head * 8;
;             const f32x4 s0 = gld<f32x4>(sp); float ssum = (s0[0] + s0[1]) + (s0[2] + s0[3]);
;             if (g.dvshift == 9) { const f32x4 s1 = gld<f32x4>(sp + 4); ssum += (s1[0] + s1[1]) + (s1[2] + s1[3]); }
;             rs = rsqrtf(ssum * (g.dvshift == 9 ? (1.0f / 512.0f) : (1.0f / 256.0f)) + EPS); }
;           bf16_t* op = g.o0 + (size_t)row * N + col;
;           const u32x4 ow = gld<u32x4>(op);
;           const float ru = gld<float>(g.rowscale + row);
;           const f32x4 v0 = acc[ai][bj][m][0] * ru, v1 = acc[ai][bj][m][1] * ru;
;           float o[8] = {bflo(ow.x), bfhi(ow.x), bflo(ow.y), bfhi(ow.y), bflo(ow.z), bfhi(ow.z), bflo(ow.w), bfhi(ow.w)};
; #pragma unroll
;           for (int j = 0; j < 4; ++j) { o[j] = o[j] * rs * g0[j] * v0[j] * sigmoidf_(v0[j]); o[4 + j] = o[4 + j] * rs * g1[j] * v1[j] * sigmoidf_(v1[j]); }
;           u32x4 w; w.x = pk(o[0], o[1]); w.y = pk(o[2], o[3]); w.z = pk(o[4], o[5]); w.w = pk(o[6], o[7]);
;           gst<u32x4>(op, w);
	v_mov_b64_e32 v[172:173], v[232:233]
	v_mov_b64_e32 v[174:175], v[234:235]
	s_mov_b32 s26, 0x3b000000
	v_mov_b32_e32 v176, v173
	v_mov_b32_e32 v177, v174
	v_mov_b32_e32 v173, v175
	v_pk_add_f32 v[172:173], v[176:177], v[172:173]
	s_nop 0
	v_add_f32_e32 v139, v172, v173
	v_add_f32_e32 v138, v138, v139
.LBB0_227:
	v_fma_f32 v138, s26, v138, v204
	v_cmp_gt_f32_e32 vcc, s33, v138
	v_mul_f32_e32 v139, 0x4b800000, v138
	s_nop 0
	v_cndmask_b32_e32 v138, v138, v139, vcc
	v_rsq_f32_e32 v138, v138
	s_nop 0
	v_mul_f32_e32 v139, 0x45800000, v138
	v_cndmask_b32_e32 v148, v138, v139, vcc
	v_mad_u64_u32 v[138:139], s[26:27], v136, s70, 0
	v_mov_b32_e32 v136, v139
	v_mad_u64_u32 v[136:137], s[26:27], v137, s70, v[136:137]
	v_mov_b32_e32 v139, v136
	v_lshl_add_u64 v[136:137], v[138:139], 1, s[64:65]
	v_lshl_add_u64 v[172:173], v[164:165], 1, v[136:137]
	global_load_dwordx4 v[136:139], v[172:173], off
	global_load_dword v174, v[140:141], off offset:192
	s_waitcnt vmcnt(1)
	v_lshlrev_b32_e32 v176, 16, v136
	s_waitcnt vmcnt(0)
	v_pk_mul_f32 v[178:179], v[100:101], v[174:175] op_sel_hi:[1,0]
	v_and_b32_e32 v177, 0xffff0000, v136
	v_mul_f32_e32 v136, 0xbfb8aa3b, v178
	v_exp_f32_e32 v190, v136
	v_mul_f32_e32 v136, 0xbfb8aa3b, v179
	v_exp_f32_e32 v191, v136
	v_pk_mul_f32 v[176:177], v[148:149], v[176:177] op_sel_hi:[0,1]
	v_pk_mul_f32 v[176:177], v[132:133], v[176:177]
	s_nop 0
	v_pk_mul_f32 v[176:177], v[178:179], v[176:177]
	v_pk_add_f32 v[178:179], v[190:191], 1.0 op_sel_hi:[1,0]
	s_nop 0
	v_div_scale_f32 v136, s[26:27], v179, v179, 1.0
	v_rcp_f32_e32 v167, v136
	s_nop 0
	v_fma_f32 v175, -v136, v167, 1.0
	v_fmac_f32_e32 v167, v175, v167
	v_div_scale_f32 v175, vcc, 1.0, v179, 1.0
	v_mul_f32_e32 v190, v175, v167
	v_fma_f32 v191, -v136, v190, v175
	v_fmac_f32_e32 v190, v191, v167
	v_fma_f32 v136, -v136, v190, v175
	v_div_fmas_f32 v136, v136, v167, v190
	v_div_fixup_f32 v179, v136, v179, 1.0
	v_div_scale_f32 v136, s[26:27], v178, v178, 1.0
	v_rcp_f32_e32 v167, v136
	s_nop 0
	v_fma_f32 v175, -v136, v167, 1.0
	v_fmac_f32_e32 v167, v175, v167
	v_div_scale_f32 v175, vcc, 1.0, v178, 1.0
	v_mul_f32_e32 v190, v175, v167
	v_fma_f32 v191, -v136, v190, v175
	v_fmac_f32_e32 v190, v191, v167
	v_fma_f32 v136, -v136, v190, v175
	v_div_fmas_f32 v136, v136, v167, v190
	v_pk_mul_f32 v[190:191], v[96:97], v[174:175] op_sel_hi:[1,0]
	v_div_fixup_f32 v178, v136, v178, 1.0
	v_mul_f32_e32 v136, 0xbfb8aa3b, v190
	v_exp_f32_e32 v192, v136
	v_mul_f32_e32 v136, 0xbfb8aa3b, v191
	v_exp_f32_e32 v193, v136
	v_pk_mul_f32 v[176:177], v[178:179], v[176:177]
	v_lshlrev_b32_e32 v178, 16, v138
	v_and_b32_e32 v179, 0xffff0000, v138
	v_pk_mul_f32 v[178:179], v[148:149], v[178:179] op_sel_hi:[0,1]
	v_pk_mul_f32 v[178:179], v[128:129], v[178:179]
	s_nop 0
	v_pk_mul_f32 v[178:179], v[190:191], v[178:179]
	v_pk_add_f32 v[190:191], v[192:193], 1.0 op_sel_hi:[1,0]
	s_nop 0
	v_div_scale_f32 v136, s[26:27], v191, v191, 1.0
	v_rcp_f32_e32 v138, v136
	s_nop 0
	v_fma_f32 v167, -v136, v138, 1.0
	v_fmac_f32_e32 v138, v167, v138
	v_div_scale_f32 v167, vcc, 1.0, v191, 1.0
	v_mul_f32_e32 v175, v167, v138
	v_fma_f32 v192, -v136, v175, v167
	v_fmac_f32_e32 v175, v192, v138
	v_fma_f32 v136, -v136, v175, v167
	v_div_fmas_f32 v136, v136, v138, v175
	v_div_fixup_f32 v191, v136, v191, 1.0
	v_div_scale_f32 v136, s[26:27], v190, v190, 1.0
	v_rcp_f32_e32 v138, v136
	s_nop 0
	v_fma_f32 v167, -v136, v138, 1.0
	v_fmac_f32_e32 v138, v167, v138
	v_div_scale_f32 v167, vcc, 1.0, v190, 1.0
	v_mul_f32_e32 v175, v167, v138
	v_fma_f32 v192, -v136, v175, v167
	v_fmac_f32_e32 v175, v192, v138
	v_fma_f32 v136, -v136, v175, v167
	v_div_fmas_f32 v136, v136, v138, v175
	v_pk_mul_f32 v[192:193], v[102:103], v[174:175] op_sel_hi:[1,0]
	v_div_fixup_f32 v190, v136, v190, 1.0
	v_mul_f32_e32 v138, 0xbfb8aa3b, v192
	v_pk_mul_f32 v[178:179], v[190:191], v[178:179]
	v_exp_f32_e32 v190, v138
	v_mul_f32_e32 v138, 0xbfb8aa3b, v193
	v_exp_f32_e32 v191, v138
	v_lshlrev_b32_e32 v136, 16, v137
	v_and_b32_e32 v137, 0xffff0000, v137
	v_pk_mul_f32 v[136:137], v[148:149], v[136:137] op_sel_hi:[0,1]
	v_pk_add_f32 v[190:191], v[190:191], 1.0 op_sel_hi:[1,0]
	v_pk_mul_f32 v[136:137], v[134:135], v[136:137]
	v_div_scale_f32 v138, s[26:27], v191, v191, 1.0
	v_rcp_f32_e32 v167, v138
	v_pk_mul_f32 v[136:137], v[192:193], v[136:137]
	v_fma_f32 v175, -v138, v167, 1.0
	v_fmac_f32_e32 v167, v175, v167
	v_div_scale_f32 v175, vcc, 1.0, v191, 1.0
	v_mul_f32_e32 v192, v175, v167
	v_fma_f32 v193, -v138, v192, v175
	v_fmac_f32_e32 v192, v193, v167
	v_fma_f32 v138, -v138, v192, v175
	v_div_fmas_f32 v138, v138, v167, v192
	v_div_fixup_f32 v191, v138, v191, 1.0
	v_div_scale_f32 v138, s[26:27], v190, v190, 1.0
	v_rcp_f32_e32 v167, v138
	s_nop 0
	v_fma_f32 v175, -v138, v167, 1.0
	v_fmac_f32_e32 v167, v175, v167
	v_div_scale_f32 v175, vcc, 1.0, v190, 1.0
	v_mul_f32_e32 v192, v175, v167
	v_fma_f32 v193, -v138, v192, v175
	v_fmac_f32_e32 v192, v193, v167
	v_fma_f32 v138, -v138, v192, v175
	v_div_fmas_f32 v138, v138, v167, v192
	v_div_fixup_f32 v190, v138, v190, 1.0
	v_pk_mul_f32 v[190:191], v[190:191], v[136:137]
	v_lshlrev_b32_e32 v136, 16, v139
	v_and_b32_e32 v137, 0xffff0000, v139
	v_pk_mul_f32 v[136:137], v[148:149], v[136:137] op_sel_hi:[0,1]
	v_pk_mul_f32 v[138:139], v[98:99], v[174:175] op_sel_hi:[1,0]
	v_pk_mul_f32 v[136:137], v[130:131], v[136:137]
	v_mul_f32_e32 v167, 0xbfb8aa3b, v138
	v_pk_mul_f32 v[136:137], v[138:139], v[136:137]
	v_mul_f32_e32 v138, 0xbfb8aa3b, v139
	v_exp_f32_e32 v174, v167
	v_exp_f32_e32 v175, v138
	s_nop 0
	v_pk_add_f32 v[138:139], v[174:175], 1.0 op_sel_hi:[1,0]
	s_nop 0
	v_div_scale_f32 v148, s[26:27], v139, v139, 1.0
	v_rcp_f32_e32 v167, v148
	s_nop 0
	v_fma_f32 v174, -v148, v167, 1.0
	v_fmac_f32_e32 v167, v174, v167
	v_div_scale_f32 v174, vcc, 1.0, v139, 1.0
	v_mul_f32_e32 v175, v174, v167
	v_fma_f32 v192, -v148, v175, v174
	v_fmac_f32_e32 v175, v192, v167
	v_fma_f32 v148, -v148, v175, v174
	v_div_fmas_f32 v148, v148, v167, v175
	v_div_fixup_f32 v139, v148, v139, 1.0
	v_div_scale_f32 v148, s[26:27], v138, v138, 1.0
	v_rcp_f32_e32 v167, v148
	s_mov_b32 s26, 0x3b800000
	s_mov_b32 s27, 0x3b800000
	v_fma_f32 v174, -v148, v167, 1.0
	v_fmac_f32_e32 v167, v174, v167
	v_div_scale_f32 v174, vcc, 1.0, v138, 1.0
	v_mul_f32_e32 v175, v174, v167
	v_fma_f32 v192, -v148, v175, v174
	v_fmac_f32_e32 v175, v192, v167
	v_fma_f32 v148, -v148, v175, v174
	v_div_fmas_f32 v148, v148, v167, v175
	v_div_fixup_f32 v138, v148, v138, 1.0
	v_pk_mul_f32 v[174:175], v[138:139], v[136:137]
	v_cvt_pk_bf16_f32 v136, v176, v177
	v_cvt_pk_bf16_f32 v137, v190, v191
	v_cvt_pk_bf16_f32 v138, v178, v179
	v_cvt_pk_bf16_f32 v139, v174, v175
	global_store_dwordx4 v[172:173], v[136:139], off
	s_and_b64 vcc, exec, s[44:45]
	s_nop 0
	v_add_u32_e32 v136, 0x80, v166
	v_ashrrev_i32_e32 v137, 31, v136
	v_lshlrev_b64 v[138:139], 7, v[136:137]
	v_lshl_add_u64 v[190:191], s[66:67], 0, v[138:139]
	v_lshl_add_u64 v[174:175], v[180:181], 2, v[190:191]
	global_load_dwordx4 v[176:179], v[174:175], off
	global_load_dwordx4 v[232:235], v[174:175], off offset:16
	s_waitcnt vmcnt(0)
; DI unsigned pk(float lo, float hi) { f32x2 v = {lo, hi}; bf2_t b = __builtin_convertvector(v, bf2_t); return __builtin_bit_cast(unsigned, b); }
; DI float bflo(unsigned w) { return __uint_as_float(w << 16); }
; DI float bfhi(unsigned w) { return __uint_as_float(w & 0xffff0000u); }
; DI float sigmoidf_(float x) { return 1.0f / (1.0f + __expf(-x)); }
; DI void gemm_epilogue(const GemmDesc& g, f32x4 (&acc)[2][2][4][2], int brow, int bcol, int wr, int wc, int fr, int fq) {
;     ...
;           const int row = rowb + ai * HALF + m * 16;
;           float rs;
;           { const float* sp = g.f0 + (size_t)row * 32 + head * 8;
;             const f32x4 s0 = gld<f32x4>(sp); float ssum = (s0[0] + s0[1]) + (s0[2] + s0[3]);
;             if (g.dvshift == 9) { const f32x4 s1 = gld<f32x4>(sp + 4); ssum += (s1[0] + s1[1]) + (s1[2] + s1[3]); }
;             rs = rsqrtf(ssum * (g.dvshift == 9 ? (1.0f / 512.0f) : (1.0f / 256.0f)) + EPS); }
;           bf16_t* op = g.o0 + (size_t)row * N + col;
;           const u32x4 ow = gld<u32x4>(op);
;           const float ru = gld<float>(g.rowscale + row);
;           const f32x4 v0 = acc[ai][bj][m][0] * ru, v1 = acc[ai][bj][m][1] * ru;
;           float o[8] = {bflo(ow.x), bfhi(ow.x), bflo(ow.y), bfhi(ow.y), bflo(ow.z), bfhi(ow.z), bflo(ow.w), bfhi(ow.w)};
; #pragma unroll
;           for (int j = 0; j < 4; ++j) { o[j] = o[j] * rs * g0[j] * v0[j] * sigmoidf_(v0[j]); o[4 + j] = o[4 + j] * rs * g1[j] * v1[j] * sigmoidf_(v1[j]); }
;           u32x4 w; w.x = pk(o[0], o[1]); w.y = pk(o[2], o[3]); w.z = pk(o[4], o[5]); w.w = pk(o[6], o[7]);
;           gst<u32x4>(op, w);
	v_mov_b32_e32 v138, v177
	v_mov_b32_e32 v139, v178
	v_mov_b32_e32 v177, v179
	v_pk_add_f32 v[138:139], v[138:139], v[176:177]
	s_nop 0
	v_pk_add_f32 v[138:139], v[138:139], v[138:139] op_sel:[0,1] op_sel_hi:[1,0]
	s_cbranch_vccnz .LBB0_229
	v_mov_b64_e32 v[174:175], v[232:233]
	v_mov_b64_e32 v[176:177], v[234:235]
	s_mov_b32 s27, 0x3b000000
	v_mov_b32_e32 v178, v175
	v_mov_b32_e32 v179, v176
	v_mov_b32_e32 v175, v177
	v_pk_add_f32 v[174:175], v[178:179], v[174:175]
	s_nop 0
	v_add_f32_e32 v139, v174, v175
	v_add_f32_e32 v138, v138, v139
.LBB0_229:
	v_fma_f32 v138, s27, v138, v204
	v_cmp_gt_f32_e32 vcc, s33, v138
	v_mul_f32_e32 v139, 0x4b800000, v138
	s_nop 0
	v_cndmask_b32_e32 v138, v138, v139, vcc
	v_rsq_f32_e32 v138, v138
	s_nop 0
	v_mul_f32_e32 v139, 0x45800000, v138
	v_cndmask_b32_e32 v148, v138, v139, vcc
	v_mad_u64_u32 v[138:139], vcc, v136, s70, 0
	v_mov_b32_e32 v136, v139
	v_mad_u64_u32 v[136:137], vcc, v137, s70, v[136:137]
	v_mov_b32_e32 v139, v136
	v_lshl_add_u64 v[136:137], v[138:139], 1, s[64:65]
	v_lshl_add_u64 v[174:175], v[164:165], 1, v[136:137]
	global_load_dwordx4 v[136:139], v[174:175], off
	global_load_dword v176, v[140:141], off offset:512
	s_waitcnt vmcnt(1)
	v_lshlrev_b32_e32 v178, 16, v136
	s_waitcnt vmcnt(0)
	v_pk_mul_f32 v[192:193], v[92:93], v[176:177] op_sel_hi:[1,0]
	v_and_b32_e32 v179, 0xffff0000, v136
	v_mul_f32_e32 v136, 0xbfb8aa3b, v192
	v_exp_f32_e32 v194, v136
	v_mul_f32_e32 v136, 0xbfb8aa3b, v193
	v_exp_f32_e32 v195, v136
	v_pk_mul_f32 v[178:179], v[148:149], v[178:179] op_sel_hi:[0,1]
	v_pk_mul_f32 v[178:179], v[132:133], v[178:179]
	s_nop 0
	v_pk_mul_f32 v[178:179], v[192:193], v[178:179]
	v_pk_add_f32 v[192:193], v[194:195], 1.0 op_sel_hi:[1,0]
	s_nop 0
	v_div_scale_f32 v136, vcc, v193, v193, 1.0
	v_rcp_f32_e32 v167, v136
	s_nop 0
	v_fma_f32 v177, -v136, v167, 1.0
	v_fmac_f32_e32 v167, v177, v167
	v_div_scale_f32 v177, vcc, 1.0, v193, 1.0
	v_mul_f32_e32 v194, v177, v167
	v_fma_f32 v195, -v136, v194, v177
	v_fmac_f32_e32 v194, v195, v167
	v_fma_f32 v136, -v136, v194, v177
	v_div_fmas_f32 v136, v136, v167, v194
	v_div_fixup_f32 v193, v136, v193, 1.0
	v_div_scale_f32 v136, vcc, v192, v192, 1.0
	v_rcp_f32_e32 v167, v136
	s_nop 0
	v_fma_f32 v177, -v136, v167, 1.0
	v_fmac_f32_e32 v167, v177, v167
	v_div_scale_f32 v177, vcc, 1.0, v192, 1.0
	v_mul_f32_e32 v194, v177, v167
	v_fma_f32 v195, -v136, v194, v177
	v_fmac_f32_e32 v194, v195, v167
	v_fma_f32 v136, -v136, v194, v177
	v_div_fmas_f32 v136, v136, v167, v194
	v_pk_mul_f32 v[194:195], v[88:89], v[176:177] op_sel_hi:[1,0]
	v_div_fixup_f32 v192, v136, v192, 1.0
	v_mul_f32_e32 v136, 0xbfb8aa3b, v194
	v_exp_f32_e32 v196, v136
	v_mul_f32_e32 v136, 0xbfb8aa3b, v195
	v_exp_f32_e32 v197, v136
	v_pk_mul_f32 v[178:179], v[192:193], v[178:179]
	v_lshlrev_b32_e32 v192, 16, v138
	v_and_b32_e32 v193, 0xffff0000, v138
	v_pk_mul_f32 v[192:193], v[148:149], v[192:193] op_sel_hi:[0,1]
	v_pk_mul_f32 v[192:193], v[128:129], v[192:193]
	s_nop 0
	v_pk_mul_f32 v[192:193], v[194:195], v[192:193]
	v_pk_add_f32 v[194:195], v[196:197], 1.0 op_sel_hi:[1,0]
	s_nop 0
	v_div_scale_f32 v136, vcc, v195, v195, 1.0
	v_rcp_f32_e32 v138, v136
	s_nop 0
	v_fma_f32 v167, -v136, v138, 1.0
	v_fmac_f32_e32 v138, v167, v138
	v_div_scale_f32 v167, vcc, 1.0, v195, 1.0
	v_mul_f32_e32 v177, v167, v138
	v_fma_f32 v196, -v136, v177, v167
	v_fmac_f32_e32 v177, v196, v138
	v_fma_f32 v136, -v136, v177, v167
	v_div_fmas_f32 v136, v136, v138, v177
	v_div_fixup_f32 v195, v136, v195, 1.0
	v_div_scale_f32 v136, vcc, v194, v194, 1.0
	v_rcp_f32_e32 v138, v136
	s_nop 0
	v_fma_f32 v167, -v136, v138, 1.0
	v_fmac_f32_e32 v138, v167, v138
	v_div_scale_f32 v167, vcc, 1.0, v194, 1.0
	v_mul_f32_e32 v177, v167, v138
	v_fma_f32 v196, -v136, v177, v167
	v_fmac_f32_e32 v177, v196, v138
	v_fma_f32 v136, -v136, v177, v167
	v_div_fmas_f32 v136, v136, v138, v177
	v_pk_mul_f32 v[196:197], v[94:95], v[176:177] op_sel_hi:[1,0]
	v_div_fixup_f32 v194, v136, v194, 1.0
	v_mul_f32_e32 v138, 0xbfb8aa3b, v196
	v_pk_mul_f32 v[192:193], v[194:195], v[192:193]
	v_exp_f32_e32 v194, v138
	v_mul_f32_e32 v138, 0xbfb8aa3b, v197
	v_exp_f32_e32 v195, v138
	v_lshlrev_b32_e32 v136, 16, v137
	v_and_b32_e32 v137, 0xffff0000, v137
	v_pk_mul_f32 v[136:137], v[148:149], v[136:137] op_sel_hi:[0,1]
	v_pk_add_f32 v[194:195], v[194:195], 1.0 op_sel_hi:[1,0]
	v_pk_mul_f32 v[136:137], v[134:135], v[136:137]
	v_div_scale_f32 v138, vcc, v195, v195, 1.0
	v_rcp_f32_e32 v167, v138
	v_pk_mul_f32 v[136:137], v[196:197], v[136:137]
	v_fma_f32 v177, -v138, v167, 1.0
	v_fmac_f32_e32 v167, v177, v167
	v_div_scale_f32 v177, vcc, 1.0, v195, 1.0
	v_mul_f32_e32 v196, v177, v167
	v_fma_f32 v197, -v138, v196, v177
	v_fmac_f32_e32 v196, v197, v167
	v_fma_f32 v138, -v138, v196, v177
	v_div_fmas_f32 v138, v138, v167, v196
	v_div_fixup_f32 v195, v138, v195, 1.0
	v_div_scale_f32 v138, vcc, v194, v194, 1.0
	v_rcp_f32_e32 v167, v138
	s_nop 0
	v_fma_f32 v177, -v138, v167, 1.0
	v_fmac_f32_e32 v167, v177, v167
	v_div_scale_f32 v177, vcc, 1.0, v194, 1.0
	v_mul_f32_e32 v196, v177, v167
	v_fma_f32 v197, -v138, v196, v177
	v_fmac_f32_e32 v196, v197, v167
	v_fma_f32 v138, -v138, v196, v177
	v_div_fmas_f32 v138, v138, v167, v196
	v_div_fixup_f32 v194, v138, v194, 1.0
	v_pk_mul_f32 v[194:195], v[194:195], v[136:137]
	v_lshlrev_b32_e32 v136, 16, v139
	v_and_b32_e32 v137, 0xffff0000, v139
	v_pk_mul_f32 v[136:137], v[148:149], v[136:137] op_sel_hi:[0,1]
	v_pk_mul_f32 v[138:139], v[90:91], v[176:177] op_sel_hi:[1,0]
	v_pk_mul_f32 v[136:137], v[130:131], v[136:137]
	v_mul_f32_e32 v167, 0xbfb8aa3b, v138
	v_pk_mul_f32 v[136:137], v[138:139], v[136:137]
	v_mul_f32_e32 v138, 0xbfb8aa3b, v139
; DI unsigned pk(float lo, float hi) { f32x2 v = {lo, hi}; bf2_t b = __builtin_convertvector(v, bf2_t); return __builtin_bit_cast(unsigned, b); }
; DI float bflo(unsigned w) { return __uint_as_float(w << 16); }
; DI float bfhi(unsigned w) { return __uint_as_float(w & 0xffff0000u); }
; DI float sigmoidf_(float x) { return 1.0f / (1.0f + __expf(-x)); }
; DI void gemm_epilogue(const GemmDesc& g, f32x4 (&acc)[2][2][4][2], int brow, int bcol, int wr, int wc, int fr, int fq) {
;     ...
;           const int row = rowb + ai * HALF + m * 16;
;           float rs;
;           { const float* sp = g.f0 + (size_t)row * 32 + head * 8;
;             const f32x4 s0 = gld<f32x4>(sp); float ssum = (s0[0] + s0[1]) + (s0[2] + s0[3]);
;             if (g.dvshift == 9) { const f32x4 s1 = gld<f32x4>(sp + 4); ssum += (s1[0] + s1[1]) + (s1[2] + s1[3]); }
;             rs = rsqrtf(ssum * (g.dvshift == 9 ? (1.0f / 512.0f) : (1.0f / 256.0f)) + EPS); }
;           bf16_t* op = g.o0 + (size_t)row * N + col;
;           const u32x4 ow = gld<u32x4>(op);
;           const float ru = gld<float>(g.rowscale + row);
;           const f32x4 v0 = acc[ai][bj][m][0] * ru, v1 = acc[ai][bj][m][1] * ru;
;           float o[8] = {bflo(ow.x), bfhi(ow.x), bflo(ow.y), bfhi(ow.y), bflo(ow.z), bfhi(ow.z), bflo(ow.w), bfhi(ow.w)};
; #pragma unroll
;           for (int j = 0; j < 4; ++j) { o[j] = o[j] * rs * g0[j] * v0[j] * sigmoidf_(v0[j]); o[4 + j] = o[4 + j] * rs * g1[j] * v1[j] * sigmoidf_(v1[j]); }
;           u32x4 w; w.x = pk(o[0], o[1]); w.y = pk(o[2], o[3]); w.z = pk(o[4], o[5]); w.w = pk(o[6], o[7]);
;           gst<u32x4>(op, w);
	v_exp_f32_e32 v176, v167
	v_exp_f32_e32 v177, v138
	s_nop 0
	v_pk_add_f32 v[138:139], v[176:177], 1.0 op_sel_hi:[1,0]
	s_nop 0
	v_div_scale_f32 v148, vcc, v139, v139, 1.0
	v_rcp_f32_e32 v167, v148
	s_nop 0
	v_fma_f32 v176, -v148, v167, 1.0
	v_fmac_f32_e32 v167, v176, v167
	v_div_scale_f32 v176, vcc, 1.0, v139, 1.0
	v_mul_f32_e32 v177, v176, v167
	v_fma_f32 v196, -v148, v177, v176
	v_fmac_f32_e32 v177, v196, v167
	v_fma_f32 v148, -v148, v177, v176
	v_div_fmas_f32 v148, v148, v167, v177
	v_div_fixup_f32 v139, v148, v139, 1.0
	v_div_scale_f32 v148, vcc, v138, v138, 1.0
	v_rcp_f32_e32 v167, v148
	s_nop 0
	v_fma_f32 v176, -v148, v167, 1.0
	v_fmac_f32_e32 v167, v176, v167
	v_div_scale_f32 v176, vcc, 1.0, v138, 1.0
	v_mul_f32_e32 v177, v176, v167
	v_fma_f32 v196, -v148, v177, v176
	v_fmac_f32_e32 v177, v196, v167
	v_fma_f32 v148, -v148, v177, v176
	v_div_fmas_f32 v148, v148, v167, v177
	v_div_fixup_f32 v138, v148, v138, 1.0
	v_pk_mul_f32 v[176:177], v[138:139], v[136:137]
	v_cvt_pk_bf16_f32 v136, v178, v179
	v_cvt_pk_bf16_f32 v137, v194, v195
	v_cvt_pk_bf16_f32 v138, v192, v193
	v_cvt_pk_bf16_f32 v139, v176, v177
	global_store_dwordx4 v[174:175], v[136:139], off
	s_and_b64 vcc, exec, s[44:45]
	s_nop 0
	v_add_u32_e32 v136, 0x90, v166
	v_ashrrev_i32_e32 v137, 31, v136
	v_lshlrev_b64 v[138:139], 7, v[136:137]
	v_lshl_add_u64 v[192:193], s[66:67], 0, v[138:139]
	v_lshl_add_u64 v[176:177], v[180:181], 2, v[192:193]
	global_load_dwordx4 v[194:197], v[176:177], off
	global_load_dwordx4 v[232:235], v[176:177], off offset:16
	s_waitcnt vmcnt(0)
	v_mov_b32_e32 v138, v195
	v_mov_b32_e32 v139, v196
	v_mov_b32_e32 v195, v197
	v_pk_add_f32 v[138:139], v[138:139], v[194:195]
	s_nop 0
	v_pk_add_f32 v[138:139], v[138:139], v[138:139] op_sel:[0,1] op_sel_hi:[1,0]
	s_cbranch_vccnz .LBB0_231
	v_mov_b64_e32 v[176:177], v[232:233]
	v_mov_b64_e32 v[178:179], v[234:235]
	s_mov_b32 s26, 0x3b000000
	v_mov_b32_e32 v194, v177
	v_mov_b32_e32 v195, v178
	v_mov_b32_e32 v177, v179
	v_pk_add_f32 v[176:177], v[194:195], v[176:177]
	s_nop 0
	v_add_f32_e32 v139, v176, v177
	v_add_f32_e32 v138, v138, v139
.LBB0_231:
	v_fma_f32 v138, s26, v138, v204
	v_cmp_gt_f32_e32 vcc, s33, v138
	v_mul_f32_e32 v139, 0x4b800000, v138
	s_nop 0
	v_cndmask_b32_e32 v138, v138, v139, vcc
	v_rsq_f32_e32 v138, v138
	s_nop 0
	v_mul_f32_e32 v139, 0x45800000, v138
	v_cndmask_b32_e32 v148, v138, v139, vcc
	v_mad_u64_u32 v[138:139], s[26:27], v136, s70, 0
	v_mov_b32_e32 v136, v139
	v_mad_u64_u32 v[136:137], s[26:27], v137, s70, v[136:137]
	v_mov_b32_e32 v139, v136
	v_lshl_add_u64 v[136:137], v[138:139], 1, s[64:65]
	v_lshl_add_u64 v[176:177], v[164:165], 1, v[136:137]
	global_load_dwordx4 v[136:139], v[176:177], off
	global_load_dword v178, v[140:141], off offset:576
	s_waitcnt vmcnt(1)
	v_lshlrev_b32_e32 v194, 16, v136
	s_waitcnt vmcnt(0)
	v_pk_mul_f32 v[196:197], v[84:85], v[178:179] op_sel_hi:[1,0]
	v_and_b32_e32 v195, 0xffff0000, v136
	v_mul_f32_e32 v136, 0xbfb8aa3b, v196
	v_exp_f32_e32 v198, v136
	v_mul_f32_e32 v136, 0xbfb8aa3b, v197
	v_exp_f32_e32 v199, v136
	v_pk_mul_f32 v[194:195], v[148:149], v[194:195] op_sel_hi:[0,1]
	v_pk_mul_f32 v[194:195], v[132:133], v[194:195]
	s_nop 0
	v_pk_mul_f32 v[194:195], v[196:197], v[194:195]
	v_pk_add_f32 v[196:197], v[198:199], 1.0 op_sel_hi:[1,0]
	s_nop 0
	v_div_scale_f32 v136, s[26:27], v197, v197, 1.0
	v_rcp_f32_e32 v167, v136
	s_nop 0
	v_fma_f32 v179, -v136, v167, 1.0
	v_fmac_f32_e32 v167, v179, v167
	v_div_scale_f32 v179, vcc, 1.0, v197, 1.0
	v_mul_f32_e32 v198, v179, v167
	v_fma_f32 v199, -v136, v198, v179
	v_fmac_f32_e32 v198, v199, v167
	v_fma_f32 v136, -v136, v198, v179
	v_div_fmas_f32 v136, v136, v167, v198
	v_div_fixup_f32 v197, v136, v197, 1.0
	v_div_scale_f32 v136, s[26:27], v196, v196, 1.0
	v_rcp_f32_e32 v167, v136
	s_nop 0
	v_fma_f32 v179, -v136, v167, 1.0
	v_fmac_f32_e32 v167, v179, v167
	v_div_scale_f32 v179, vcc, 1.0, v196, 1.0
	v_mul_f32_e32 v198, v179, v167
	v_fma_f32 v199, -v136, v198, v179
	v_fmac_f32_e32 v198, v199, v167
	v_fma_f32 v136, -v136, v198, v179
	v_div_fmas_f32 v136, v136, v167, v198
	v_pk_mul_f32 v[198:199], v[80:81], v[178:179] op_sel_hi:[1,0]
	v_div_fixup_f32 v196, v136, v196, 1.0
	v_mul_f32_e32 v136, 0xbfb8aa3b, v198
	v_exp_f32_e32 v200, v136
	v_mul_f32_e32 v136, 0xbfb8aa3b, v199
	v_exp_f32_e32 v201, v136
	v_pk_mul_f32 v[194:195], v[196:197], v[194:195]
	v_lshlrev_b32_e32 v196, 16, v138
	v_and_b32_e32 v197, 0xffff0000, v138
	v_pk_mul_f32 v[196:197], v[148:149], v[196:197] op_sel_hi:[0,1]
	v_pk_mul_f32 v[196:197], v[128:129], v[196:197]
	s_nop 0
	v_pk_mul_f32 v[196:197], v[198:199], v[196:197]
	v_pk_add_f32 v[198:199], v[200:201], 1.0 op_sel_hi:[1,0]
	s_nop 0
	v_div_scale_f32 v136, s[26:27], v199, v199, 1.0
	v_rcp_f32_e32 v138, v136
	s_nop 0
	v_fma_f32 v167, -v136, v138, 1.0
	v_fmac_f32_e32 v138, v167, v138
	v_div_scale_f32 v167, vcc, 1.0, v199, 1.0
	v_mul_f32_e32 v179, v167, v138
	v_fma_f32 v200, -v136, v179, v167
	v_fmac_f32_e32 v179, v200, v138
	v_fma_f32 v136, -v136, v179, v167
	v_div_fmas_f32 v136, v136, v138, v179
	v_div_fixup_f32 v199, v136, v199, 1.0
	v_div_scale_f32 v136, s[26:27], v198, v198, 1.0
	v_rcp_f32_e32 v138, v136
	s_nop 0
	v_fma_f32 v167, -v136, v138, 1.0
	v_fmac_f32_e32 v138, v167, v138
	v_div_scale_f32 v167, vcc, 1.0, v198, 1.0
	v_mul_f32_e32 v179, v167, v138
	v_fma_f32 v200, -v136, v179, v167
	v_fmac_f32_e32 v179, v200, v138
	v_fma_f32 v136, -v136, v179, v167
	v_div_fmas_f32 v136, v136, v138, v179
	v_pk_mul_f32 v[200:201], v[86:87], v[178:179] op_sel_hi:[1,0]
	v_div_fixup_f32 v198, v136, v198, 1.0
	v_mul_f32_e32 v138, 0xbfb8aa3b, v200
	v_pk_mul_f32 v[196:197], v[198:199], v[196:197]
	v_exp_f32_e32 v198, v138
; DI unsigned pk(float lo, float hi) { f32x2 v = {lo, hi}; bf2_t b = __builtin_convertvector(v, bf2_t); return __builtin_bit_cast(unsigned, b); }
; DI float bflo(unsigned w) { return __uint_as_float(w << 16); }
; DI float bfhi(unsigned w) { return __uint_as_float(w & 0xffff0000u); }
; DI float sigmoidf_(float x) { return 1.0f / (1.0f + __expf(-x)); }
; DI void gemm_epilogue(const GemmDesc& g, f32x4 (&acc)[2][2][4][2], int brow, int bcol, int wr, int wc, int fr, int fq) {
;     ...
;           const int row = rowb + ai * HALF + m * 16;
;           float rs;
;           { const float* sp = g.f0 + (size_t)row * 32 + head * 8;
;             const f32x4 s0 = gld<f32x4>(sp); float ssum = (s0[0] + s0[1]) + (s0[2] + s0[3]);
;             if (g.dvshift == 9) { const f32x4 s1 = gld<f32x4>(sp + 4); ssum += (s1[0] + s1[1]) + (s1[2] + s1[3]); }
;             rs = rsqrtf(ssum * (g.dvshift == 9 ? (1.0f / 512.0f) : (1.0f / 256.0f)) + EPS); }
;           bf16_t* op = g.o0 + (size_t)row * N + col;
;           const u32x4 ow = gld<u32x4>(op);
;           const float ru = gld<float>(g.rowscale + row);
;           const f32x4 v0 = acc[ai][bj][m][0] * ru, v1 = acc[ai][bj][m][1] * ru;
;           float o[8] = {bflo(ow.x), bfhi(ow.x), bflo(ow.y), bfhi(ow.y), bflo(ow.z), bfhi(ow.z), bflo(ow.w), bfhi(ow.w)};
; #pragma unroll
;           for (int j = 0; j < 4; ++j) { o[j] = o[j] * rs * g0[j] * v0[j] * sigmoidf_(v0[j]); o[4 + j] = o[4 + j] * rs * g1[j] * v1[j] * sigmoidf_(v1[j]); }
;           u32x4 w; w.x = pk(o[0], o[1]); w.y = pk(o[2], o[3]); w.z = pk(o[4], o[5]); w.w = pk(o[6], o[7]);
;           gst<u32x4>(op, w);
	v_mul_f32_e32 v138, 0xbfb8aa3b, v201
	v_exp_f32_e32 v199, v138
	v_lshlrev_b32_e32 v136, 16, v137
	v_and_b32_e32 v137, 0xffff0000, v137
	v_pk_mul_f32 v[136:137], v[148:149], v[136:137] op_sel_hi:[0,1]
	v_pk_add_f32 v[198:199], v[198:199], 1.0 op_sel_hi:[1,0]
	v_pk_mul_f32 v[136:137], v[134:135], v[136:137]
	v_div_scale_f32 v138, s[26:27], v199, v199, 1.0
	v_rcp_f32_e32 v167, v138
	v_pk_mul_f32 v[136:137], v[200:201], v[136:137]
	v_fma_f32 v179, -v138, v167, 1.0
	v_fmac_f32_e32 v167, v179, v167
	v_div_scale_f32 v179, vcc, 1.0, v199, 1.0
	v_mul_f32_e32 v200, v179, v167
	v_fma_f32 v201, -v138, v200, v179
	v_fmac_f32_e32 v200, v201, v167
	v_fma_f32 v138, -v138, v200, v179
	v_div_fmas_f32 v138, v138, v167, v200
	v_div_fixup_f32 v199, v138, v199, 1.0
	v_div_scale_f32 v138, s[26:27], v198, v198, 1.0
	v_rcp_f32_e32 v167, v138
	s_nop 0
	v_fma_f32 v179, -v138, v167, 1.0
	v_fmac_f32_e32 v167, v179, v167
	v_div_scale_f32 v179, vcc, 1.0, v198, 1.0
	v_mul_f32_e32 v200, v179, v167
	v_fma_f32 v201, -v138, v200, v179
	v_fmac_f32_e32 v200, v201, v167
	v_fma_f32 v138, -v138, v200, v179
	v_div_fmas_f32 v138, v138, v167, v200
	v_div_fixup_f32 v198, v138, v198, 1.0
	v_pk_mul_f32 v[198:199], v[198:199], v[136:137]
	v_lshlrev_b32_e32 v136, 16, v139
	v_and_b32_e32 v137, 0xffff0000, v139
	v_pk_mul_f32 v[136:137], v[148:149], v[136:137] op_sel_hi:[0,1]
	v_pk_mul_f32 v[138:139], v[82:83], v[178:179] op_sel_hi:[1,0]
	v_pk_mul_f32 v[136:137], v[130:131], v[136:137]
	v_mul_f32_e32 v167, 0xbfb8aa3b, v138
	v_pk_mul_f32 v[136:137], v[138:139], v[136:137]
	v_mul_f32_e32 v138, 0xbfb8aa3b, v139
	v_exp_f32_e32 v178, v167
	v_exp_f32_e32 v179, v138
	s_nop 0
	v_pk_add_f32 v[138:139], v[178:179], 1.0 op_sel_hi:[1,0]
	s_nop 0
	v_div_scale_f32 v148, s[26:27], v139, v139, 1.0
	v_rcp_f32_e32 v167, v148
	s_nop 0
	v_fma_f32 v178, -v148, v167, 1.0
	v_fmac_f32_e32 v167, v178, v167
	v_div_scale_f32 v178, vcc, 1.0, v139, 1.0
	v_mul_f32_e32 v179, v178, v167
	v_fma_f32 v200, -v148, v179, v178
	v_fmac_f32_e32 v179, v200, v167
	v_fma_f32 v148, -v148, v179, v178
	v_div_fmas_f32 v148, v148, v167, v179
	v_div_fixup_f32 v139, v148, v139, 1.0
	v_div_scale_f32 v148, s[26:27], v138, v138, 1.0
	v_rcp_f32_e32 v167, v148
	s_mov_b32 s26, 0x3b800000
	s_mov_b32 s27, 0x3b800000
	v_fma_f32 v178, -v148, v167, 1.0
	v_fmac_f32_e32 v167, v178, v167
	v_div_scale_f32 v178, vcc, 1.0, v138, 1.0
	v_mul_f32_e32 v179, v178, v167
	v_fma_f32 v200, -v148, v179, v178
	v_fmac_f32_e32 v179, v200, v167
	v_fma_f32 v148, -v148, v179, v178
	v_div_fmas_f32 v148, v148, v167, v179
	v_div_fixup_f32 v138, v148, v138, 1.0
	v_pk_mul_f32 v[178:179], v[138:139], v[136:137]
	v_cvt_pk_bf16_f32 v136, v194, v195
	v_cvt_pk_bf16_f32 v137, v198, v199
	v_cvt_pk_bf16_f32 v138, v196, v197
	v_cvt_pk_bf16_f32 v139, v178, v179
	global_store_dwordx4 v[176:177], v[136:139], off
	s_and_b64 vcc, exec, s[44:45]
	s_nop 0
	v_add_u32_e32 v136, 0xa0, v166
	v_ashrrev_i32_e32 v137, 31, v136
	v_lshlrev_b64 v[138:139], 7, v[136:137]
	v_lshl_add_u64 v[194:195], s[66:67], 0, v[138:139]
	v_lshl_add_u64 v[178:179], v[180:181], 2, v[194:195]
	global_load_dwordx4 v[196:199], v[178:179], off
	global_load_dwordx4 v[232:235], v[178:179], off offset:16
	s_waitcnt vmcnt(0)
	v_mov_b32_e32 v138, v197
	v_mov_b32_e32 v139, v198
	v_mov_b32_e32 v197, v199
	v_pk_add_f32 v[138:139], v[138:139], v[196:197]
	s_nop 0
	v_pk_add_f32 v[138:139], v[138:139], v[138:139] op_sel:[0,1] op_sel_hi:[1,0]
	s_cbranch_vccnz .LBB0_233
	v_mov_b64_e32 v[196:197], v[232:233]
	v_mov_b64_e32 v[198:199], v[234:235]
	s_mov_b32 s27, 0x3b000000
	v_mov_b32_e32 v178, v197
	v_mov_b32_e32 v179, v198
	v_mov_b32_e32 v197, v199
	v_pk_add_f32 v[178:179], v[178:179], v[196:197]
	s_nop 0
	v_add_f32_e32 v139, v178, v179
	v_add_f32_e32 v138, v138, v139
.LBB0_233:
	v_fma_f32 v138, s27, v138, v204
	v_cmp_gt_f32_e32 vcc, s33, v138
	v_mul_f32_e32 v139, 0x4b800000, v138
	s_nop 0
	v_cndmask_b32_e32 v138, v138, v139, vcc
	v_rsq_f32_e32 v138, v138
	s_nop 0
	v_mul_f32_e32 v139, 0x45800000, v138
	v_cndmask_b32_e32 v148, v138, v139, vcc
	v_mad_u64_u32 v[138:139], vcc, v136, s70, 0
	v_mov_b32_e32 v136, v139
	v_mad_u64_u32 v[136:137], vcc, v137, s70, v[136:137]
	v_mov_b32_e32 v139, v136
	v_lshl_add_u64 v[136:137], v[138:139], 1, s[64:65]
	v_lshl_add_u64 v[178:179], v[164:165], 1, v[136:137]
	global_load_dwordx4 v[136:139], v[178:179], off
	global_load_dword v196, v[140:141], off offset:640
	s_waitcnt vmcnt(1)
	v_lshlrev_b32_e32 v198, 16, v136
	s_waitcnt vmcnt(0)
; DI unsigned pk(float lo, float hi) { f32x2 v = {lo, hi}; bf2_t b = __builtin_convertvector(v, bf2_t); return __builtin_bit_cast(unsigned, b); }
; DI float bflo(unsigned w) { return __uint_as_float(w << 16); }
; DI float bfhi(unsigned w) { return __uint_as_float(w & 0xffff0000u); }
; DI float sigmoidf_(float x) { return 1.0f / (1.0f + __expf(-x)); }
; DI void gemm_epilogue(const GemmDesc& g, f32x4 (&acc)[2][2][4][2], int brow, int bcol, int wr, int wc, int fr, int fq) {
;     ...
;           const int row = rowb + ai * HALF + m * 16;
;           float rs;
;           { const float* sp = g.f0 + (size_t)row * 32 + head * 8;
;             const f32x4 s0 = gld<f32x4>(sp); float ssum = (s0[0] + s0[1]) + (s0[2] + s0[3]);
;             if (g.dvshift == 9) { const f32x4 s1 = gld<f32x4>(sp + 4); ssum += (s1[0] + s1[1]) + (s1[2] + s1[3]); }
;             rs = rsqrtf(ssum * (g.dvshift == 9 ? (1.0f / 512.0f) : (1.0f / 256.0f)) + EPS); }
;           bf16_t* op = g.o0 + (size_t)row * N + col;
;           const u32x4 ow = gld<u32x4>(op);
;           const float ru = gld<float>(g.rowscale + row);
;           const f32x4 v0 = acc[ai][bj][m][0] * ru, v1 = acc[ai][bj][m][1] * ru;
;           float o[8] = {bflo(ow.x), bfhi(ow.x), bflo(ow.y), bfhi(ow.y), bflo(ow.z), bfhi(ow.z), bflo(ow.w), bfhi(ow.w)};
; #pragma unroll
;           for (int j = 0; j < 4; ++j) { o[j] = o[j] * rs * g0[j] * v0[j] * sigmoidf_(v0[j]); o[4 + j] = o[4 + j] * rs * g1[j] * v1[j] * sigmoidf_(v1[j]); }
;           u32x4 w; w.x = pk(o[0], o[1]); w.y = pk(o[2], o[3]); w.z = pk(o[4], o[5]); w.w = pk(o[6], o[7]);
;           gst<u32x4>(op, w);
	v_pk_mul_f32 v[200:201], v[76:77], v[196:197] op_sel_hi:[1,0]
	v_and_b32_e32 v199, 0xffff0000, v136
	v_mul_f32_e32 v136, 0xbfb8aa3b, v200
	v_exp_f32_e32 v202, v136
	v_mul_f32_e32 v136, 0xbfb8aa3b, v201
	v_exp_f32_e32 v203, v136
	v_pk_mul_f32 v[198:199], v[148:149], v[198:199] op_sel_hi:[0,1]
	v_pk_mul_f32 v[198:199], v[132:133], v[198:199]
	s_nop 0
	v_pk_mul_f32 v[198:199], v[200:201], v[198:199]
	v_pk_add_f32 v[200:201], v[202:203], 1.0 op_sel_hi:[1,0]
	s_nop 0
	v_div_scale_f32 v136, vcc, v201, v201, 1.0
	v_rcp_f32_e32 v167, v136
	s_nop 0
	v_fma_f32 v197, -v136, v167, 1.0
	v_fmac_f32_e32 v167, v197, v167
	v_div_scale_f32 v197, vcc, 1.0, v201, 1.0
	v_mul_f32_e32 v202, v197, v167
	v_fma_f32 v203, -v136, v202, v197
	v_fmac_f32_e32 v202, v203, v167
	v_fma_f32 v136, -v136, v202, v197
	v_div_fmas_f32 v136, v136, v167, v202
	v_div_fixup_f32 v201, v136, v201, 1.0
	v_div_scale_f32 v136, vcc, v200, v200, 1.0
	v_rcp_f32_e32 v167, v136
	s_nop 0
	v_fma_f32 v197, -v136, v167, 1.0
	v_fmac_f32_e32 v167, v197, v167
	v_div_scale_f32 v197, vcc, 1.0, v200, 1.0
	v_mul_f32_e32 v202, v197, v167
	v_fma_f32 v203, -v136, v202, v197
	v_fmac_f32_e32 v202, v203, v167
	v_fma_f32 v136, -v136, v202, v197
	v_div_fmas_f32 v136, v136, v167, v202
	v_pk_mul_f32 v[202:203], v[72:73], v[196:197] op_sel_hi:[1,0]
	v_div_fixup_f32 v200, v136, v200, 1.0
	v_mul_f32_e32 v136, 0xbfb8aa3b, v202
	v_exp_f32_e32 v212, v136
	v_mul_f32_e32 v136, 0xbfb8aa3b, v203
	v_exp_f32_e32 v213, v136
	v_pk_mul_f32 v[198:199], v[200:201], v[198:199]
	v_lshlrev_b32_e32 v200, 16, v138
	v_and_b32_e32 v201, 0xffff0000, v138
	v_pk_mul_f32 v[200:201], v[148:149], v[200:201] op_sel_hi:[0,1]
	v_pk_mul_f32 v[200:201], v[128:129], v[200:201]
	s_nop 0
	v_pk_mul_f32 v[200:201], v[202:203], v[200:201]
	v_pk_add_f32 v[202:203], v[212:213], 1.0 op_sel_hi:[1,0]
	s_nop 0
	v_div_scale_f32 v136, vcc, v203, v203, 1.0
	v_rcp_f32_e32 v138, v136
	s_nop 0
	v_fma_f32 v167, -v136, v138, 1.0
	v_fmac_f32_e32 v138, v167, v138
	v_div_scale_f32 v167, vcc, 1.0, v203, 1.0
	v_mul_f32_e32 v197, v167, v138
	v_fma_f32 v212, -v136, v197, v167
	v_fmac_f32_e32 v197, v212, v138
	v_fma_f32 v136, -v136, v197, v167
	v_div_fmas_f32 v136, v136, v138, v197
	v_div_fixup_f32 v203, v136, v203, 1.0
	v_div_scale_f32 v136, vcc, v202, v202, 1.0
	v_rcp_f32_e32 v138, v136
	s_nop 0
	v_fma_f32 v167, -v136, v138, 1.0
	v_fmac_f32_e32 v138, v167, v138
	v_div_scale_f32 v167, vcc, 1.0, v202, 1.0
	v_mul_f32_e32 v197, v167, v138
	v_fma_f32 v212, -v136, v197, v167
	v_fmac_f32_e32 v197, v212, v138
	v_fma_f32 v136, -v136, v197, v167
	v_div_fmas_f32 v136, v136, v138, v197
	v_pk_mul_f32 v[212:213], v[78:79], v[196:197] op_sel_hi:[1,0]
	v_div_fixup_f32 v202, v136, v202, 1.0
	v_mul_f32_e32 v138, 0xbfb8aa3b, v212
	v_pk_mul_f32 v[200:201], v[202:203], v[200:201]
	v_exp_f32_e32 v202, v138
	v_mul_f32_e32 v138, 0xbfb8aa3b, v213
	v_exp_f32_e32 v203, v138
	v_lshlrev_b32_e32 v136, 16, v137
	v_and_b32_e32 v137, 0xffff0000, v137
	v_pk_mul_f32 v[136:137], v[148:149], v[136:137] op_sel_hi:[0,1]
	v_pk_add_f32 v[202:203], v[202:203], 1.0 op_sel_hi:[1,0]
	v_pk_mul_f32 v[136:137], v[134:135], v[136:137]
	v_div_scale_f32 v138, vcc, v203, v203, 1.0
	v_rcp_f32_e32 v167, v138
	v_pk_mul_f32 v[136:137], v[212:213], v[136:137]
	v_fma_f32 v197, -v138, v167, 1.0
	v_fmac_f32_e32 v167, v197, v167
	v_div_scale_f32 v197, vcc, 1.0, v203, 1.0
	v_mul_f32_e32 v212, v197, v167
	v_fma_f32 v213, -v138, v212, v197
	v_fmac_f32_e32 v212, v213, v167
	v_fma_f32 v138, -v138, v212, v197
	v_div_fmas_f32 v138, v138, v167, v212
	v_div_fixup_f32 v203, v138, v203, 1.0
	v_div_scale_f32 v138, vcc, v202, v202, 1.0
	v_rcp_f32_e32 v167, v138
	s_nop 0
	v_fma_f32 v197, -v138, v167, 1.0
	v_fmac_f32_e32 v167, v197, v167
	v_div_scale_f32 v197, vcc, 1.0, v202, 1.0
	v_mul_f32_e32 v212, v197, v167
	v_fma_f32 v213, -v138, v212, v197
	v_fmac_f32_e32 v212, v213, v167
	v_fma_f32 v138, -v138, v212, v197
	v_div_fmas_f32 v138, v138, v167, v212
	v_div_fixup_f32 v202, v138, v202, 1.0
	v_pk_mul_f32 v[202:203], v[202:203], v[136:137]
	v_lshlrev_b32_e32 v136, 16, v139
	v_and_b32_e32 v137, 0xffff0000, v139
	v_pk_mul_f32 v[136:137], v[148:149], v[136:137] op_sel_hi:[0,1]
	v_pk_mul_f32 v[138:139], v[74:75], v[196:197] op_sel_hi:[1,0]
	v_pk_mul_f32 v[136:137], v[130:131], v[136:137]
	v_mul_f32_e32 v167, 0xbfb8aa3b, v138
	v_pk_mul_f32 v[136:137], v[138:139], v[136:137]
	v_mul_f32_e32 v138, 0xbfb8aa3b, v139
	v_exp_f32_e32 v196, v167
	v_exp_f32_e32 v197, v138
	s_nop 0
	v_pk_add_f32 v[138:139], v[196:197], 1.0 op_sel_hi:[1,0]
	s_nop 0
	v_div_scale_f32 v148, vcc, v139, v139, 1.0
	v_rcp_f32_e32 v167, v148
	s_nop 0
	v_fma_f32 v196, -v148, v167, 1.0
	v_fmac_f32_e32 v167, v196, v167
	v_div_scale_f32 v196, vcc, 1.0, v139, 1.0
	v_mul_f32_e32 v197, v196, v167
	v_fma_f32 v212, -v148, v197, v196
	v_fmac_f32_e32 v197, v212, v167
	v_fma_f32 v148, -v148, v197, v196
	v_div_fmas_f32 v148, v148, v167, v197
	v_div_fixup_f32 v139, v148, v139, 1.0
	v_div_scale_f32 v148, vcc, v138, v138, 1.0
	v_rcp_f32_e32 v167, v148
	s_nop 0
	v_fma_f32 v196, -v148, v167, 1.0
	v_fmac_f32_e32 v167, v196, v167
	v_div_scale_f32 v196, vcc, 1.0, v138, 1.0
	v_mul_f32_e32 v197, v196, v167
	v_fma_f32 v212, -v148, v197, v196
	v_fmac_f32_e32 v197, v212, v167
	v_fma_f32 v148, -v148, v197, v196
	v_div_fmas_f32 v148, v148, v167, v197
	v_div_fixup_f32 v138, v148, v138, 1.0
	v_pk_mul_f32 v[196:197], v[138:139], v[136:137]
	v_cvt_pk_bf16_f32 v136, v198, v199
	v_cvt_pk_bf16_f32 v137, v202, v203
	v_cvt_pk_bf16_f32 v138, v200, v201
	v_cvt_pk_bf16_f32 v139, v196, v197
	global_store_dwordx4 v[178:179], v[136:139], off
	s_and_b64 vcc, exec, s[44:45]
	s_nop 0
	v_add_u32_e32 v136, 0xb0, v166
	v_ashrrev_i32_e32 v137, 31, v136
	v_lshlrev_b64 v[138:139], 7, v[136:137]
	v_lshl_add_u64 v[196:197], s[66:67], 0, v[138:139]
	v_lshl_add_u64 v[180:181], v[180:181], 2, v[196:197]
	global_load_dwordx4 v[198:201], v[180:181], off
	global_load_dwordx4 v[232:235], v[180:181], off offset:16
	s_waitcnt vmcnt(0)
	v_mov_b32_e32 v138, v199
	v_mov_b32_e32 v139, v200
	v_mov_b32_e32 v199, v201
	v_pk_add_f32 v[138:139], v[138:139], v[198:199]
	s_nop 0
	v_pk_add_f32 v[138:139], v[138:139], v[138:139] op_sel:[0,1] op_sel_hi:[1,0]
	s_cbranch_vccnz .LBB0_235
	v_mov_b64_e32 v[198:199], v[232:233]
	v_mov_b64_e32 v[200:201], v[234:235]
	s_mov_b32 s26, 0x3b000000
	v_mov_b32_e32 v180, v199
	v_mov_b32_e32 v181, v200
	v_mov_b32_e32 v199, v201
	v_pk_add_f32 v[180:181], v[180:181], v[198:199]
	s_nop 0
	v_add_f32_e32 v139, v180, v181
	v_add_f32_e32 v138, v138, v139

; DI unsigned pk(float lo, float hi) { f32x2 v = {lo, hi}; bf2_t b = __builtin_convertvector(v, bf2_t); return __builtin_bit_cast(unsigned, b); }
; DI float bflo(unsigned w) { return __uint_as_float(w << 16); }
; DI float bfhi(unsigned w) { return __uint_as_float(w & 0xffff0000u); }
; DI float sigmoidf_(float x) { return 1.0f / (1.0f + __expf(-x)); }
; DI void gemm_epilogue(const GemmDesc& g, f32x4 (&acc)[2][2][4][2], int brow, int bcol, int wr, int wc, int fr, int fq) {
;     ...
;       const int col = colb + bj * HALF;
;       f32x4 g0 = {1.f, 1.f, 1.f, 1.f}, g1 = g0;
;       if (g.c0) { g0 = gld<f32x4>(g.c0 + (col & dvm)); g1 = gld<f32x4>(g.c0 + (col & dvm) + 4); }
;       const int head = col >> g.dvshift;
; #pragma unroll
;       for (int ai = 0; ai < 2; ++ai)
; #pragma unroll
;         for (int m = 0; m < 4; ++m) {
;           const int row = rowb + ai * HALF + m * 16;
;           float rs;
;           { const float* sp = g.f0 + (size_t)row * 32 + head * 8;
;             const f32x4 s0 = gld<f32x4>(sp); float ssum = (s0[0] + s0[1]) + (s0[2] + s0[3]);
;             if (g.dvshift == 9) { const f32x4 s1 = gld<f32x4>(sp + 4); ssum += (s1[0] + s1[1]) + (s1[2] + s1[3]); }
;             rs = rsqrtf(ssum * (g.dvshift == 9 ? (1.0f / 512.0f) : (1.0f / 256.0f)) + EPS); }
;           bf16_t* op = g.o0 + (size_t)row * N + col;
;           const u32x4 ow = gld<u32x4>(op);
;           const float ru = gld<float>(g.rowscale + row);
;           const f32x4 v0 = acc[ai][bj][m][0] * ru, v1 = acc[ai][bj][m][1] * ru;
;           float o[8] = {bflo(ow.x), bfhi(ow.x), bflo(ow.y), bfhi(ow.y), bflo(ow.z), bfhi(ow.z), bflo(ow.w), bfhi(ow.w)};
; #pragma unroll
;           for (int j = 0; j < 4; ++j) { o[j] = o[j] * rs * g0[j] * v0[j] * sigmoidf_(v0[j]); o[4 + j] = o[4 + j] * rs * g1[j] * v1[j] * sigmoidf_(v1[j]); }
;           u32x4 w; w.x = pk(o[0], o[1]); w.y = pk(o[2], o[3]); w.z = pk(o[4], o[5]); w.w = pk(o[6], o[7]);
;           gst<u32x4>(op, w);
.LBB0_238:
	v_readlane_b32 s26, v255, 29
	s_and_b64 vcc, exec, s[44:45]
	s_mov_b32 s27, 0x3b800000
	v_ashrrev_i32_e32 v136, s26, v136
	v_lshlrev_b32_e32 v198, 3, v136
	v_ashrrev_i32_e32 v199, 31, v198
	v_lshl_add_u64 v[136:137], v[198:199], 2, v[182:183]
	global_load_dwordx4 v[200:203], v[136:137], off
	global_load_dwordx4 v[232:235], v[136:137], off offset:16
	s_mov_b32 s26, 0x3b800000
	s_waitcnt vmcnt(0)
	v_mov_b32_e32 v138, v201
	v_mov_b32_e32 v139, v202
	v_mov_b32_e32 v201, v203
	v_pk_add_f32 v[138:139], v[138:139], v[200:201]
	s_nop 0
	v_pk_add_f32 v[138:139], v[138:139], v[138:139] op_sel:[0,1] op_sel_hi:[1,0]
	s_cbranch_vccnz .LBB0_240
	v_mov_b64_e32 v[200:201], v[232:233]
	v_mov_b64_e32 v[202:203], v[234:235]
	s_mov_b32 s27, 0x3b000000
	v_mov_b32_e32 v136, v201
	v_mov_b32_e32 v137, v202
	v_mov_b32_e32 v201, v203
	v_pk_add_f32 v[136:137], v[136:137], v[200:201]
	s_nop 0
	v_add_f32_e32 v136, v136, v137
	v_add_f32_e32 v138, v138, v136
.LBB0_240:
	v_fma_f32 v136, s27, v138, v204
	v_cmp_gt_f32_e32 vcc, s33, v136
	v_mul_f32_e32 v137, 0x4b800000, v136
	s_nop 0
	v_cndmask_b32_e32 v136, v136, v137, vcc
	v_rsq_f32_e32 v136, v136
	s_nop 0
	v_mul_f32_e32 v137, 0x45800000, v136
	v_cndmask_b32_e32 v148, v136, v137, vcc
	global_load_dwordx4 v[136:139], v[142:143], off offset:256
	global_load_dword v200, v[140:141], off
	s_waitcnt vmcnt(1)
	v_lshlrev_b32_e32 v182, 16, v136
	s_waitcnt vmcnt(0)
	v_pk_mul_f32 v[202:203], v[60:61], v[200:201] op_sel_hi:[1,0]
	v_and_b32_e32 v183, 0xffff0000, v136
	v_mul_f32_e32 v136, 0xbfb8aa3b, v202
	v_exp_f32_e32 v212, v136
	v_mul_f32_e32 v136, 0xbfb8aa3b, v203
	v_exp_f32_e32 v213, v136
	v_pk_mul_f32 v[182:183], v[148:149], v[182:183] op_sel_hi:[0,1]
	v_pk_mul_f32 v[182:183], v[132:133], v[182:183]
	s_nop 0
	v_pk_mul_f32 v[182:183], v[202:203], v[182:183]
	v_pk_add_f32 v[202:203], v[212:213], 1.0 op_sel_hi:[1,0]
	s_nop 0
	v_div_scale_f32 v136, s[46:47], v203, v203, 1.0
	v_rcp_f32_e32 v165, v136
	s_nop 0
	v_fma_f32 v167, -v136, v165, 1.0
	v_fmac_f32_e32 v165, v167, v165
	v_div_scale_f32 v167, vcc, 1.0, v203, 1.0
	v_mul_f32_e32 v201, v167, v165
	v_fma_f32 v212, -v136, v201, v167
	v_fmac_f32_e32 v201, v212, v165
	v_fma_f32 v136, -v136, v201, v167
	v_div_fmas_f32 v136, v136, v165, v201
	v_div_fixup_f32 v203, v136, v203, 1.0
	v_div_scale_f32 v136, s[46:47], v202, v202, 1.0
	v_rcp_f32_e32 v165, v136
	s_nop 0
	v_fma_f32 v167, -v136, v165, 1.0
	v_fmac_f32_e32 v165, v167, v165
	v_div_scale_f32 v167, vcc, 1.0, v202, 1.0
	v_mul_f32_e32 v201, v167, v165
	v_fma_f32 v212, -v136, v201, v167
	v_fmac_f32_e32 v201, v212, v165
	v_fma_f32 v136, -v136, v201, v167
	v_div_fmas_f32 v136, v136, v165, v201
	v_pk_mul_f32 v[212:213], v[56:57], v[200:201] op_sel_hi:[1,0]
	v_div_fixup_f32 v202, v136, v202, 1.0
	v_mul_f32_e32 v136, 0xbfb8aa3b, v212
	v_exp_f32_e32 v230, v136
	v_mul_f32_e32 v136, 0xbfb8aa3b, v213
	v_exp_f32_e32 v231, v136
	v_pk_mul_f32 v[182:183], v[202:203], v[182:183]
	v_lshlrev_b32_e32 v202, 16, v138
	v_and_b32_e32 v203, 0xffff0000, v138
	v_pk_mul_f32 v[202:203], v[148:149], v[202:203] op_sel_hi:[0,1]
	v_pk_mul_f32 v[202:203], v[128:129], v[202:203]
	s_nop 0
	v_pk_mul_f32 v[202:203], v[212:213], v[202:203]
	v_pk_add_f32 v[212:213], v[230:231], 1.0 op_sel_hi:[1,0]
	s_nop 0
	v_div_scale_f32 v136, s[46:47], v213, v213, 1.0
	v_rcp_f32_e32 v138, v136
	s_nop 0
	v_fma_f32 v165, -v136, v138, 1.0
	v_fmac_f32_e32 v138, v165, v138
	v_div_scale_f32 v165, vcc, 1.0, v213, 1.0
	v_mul_f32_e32 v167, v165, v138
	v_fma_f32 v201, -v136, v167, v165
	v_fmac_f32_e32 v167, v201, v138
	v_fma_f32 v136, -v136, v167, v165
	v_div_fmas_f32 v136, v136, v138, v167
	v_div_fixup_f32 v213, v136, v213, 1.0
	v_div_scale_f32 v136, s[46:47], v212, v212, 1.0
	v_rcp_f32_e32 v138, v136
	s_nop 0
	v_fma_f32 v165, -v136, v138, 1.0
	v_fmac_f32_e32 v138, v165, v138
	v_div_scale_f32 v165, vcc, 1.0, v212, 1.0
	v_mul_f32_e32 v167, v165, v138
	v_fma_f32 v201, -v136, v167, v165
	v_fmac_f32_e32 v167, v201, v138
	v_fma_f32 v136, -v136, v167, v165
	v_div_fmas_f32 v136, v136, v138, v167
	v_div_fixup_f32 v212, v136, v212, 1.0
	v_pk_mul_f32 v[202:203], v[212:213], v[202:203]
	v_pk_mul_f32 v[212:213], v[62:63], v[200:201] op_sel_hi:[1,0]
	v_lshlrev_b32_e32 v136, 16, v137
	v_mul_f32_e32 v138, 0xbfb8aa3b, v212
	v_exp_f32_e32 v230, v138
	v_mul_f32_e32 v138, 0xbfb8aa3b, v213
	v_exp_f32_e32 v231, v138
	v_and_b32_e32 v137, 0xffff0000, v137
	v_pk_mul_f32 v[136:137], v[148:149], v[136:137] op_sel_hi:[0,1]
	v_pk_mul_f32 v[136:137], v[134:135], v[136:137]
	s_nop 0
	v_pk_mul_f32 v[136:137], v[212:213], v[136:137]
	v_pk_add_f32 v[212:213], v[230:231], 1.0 op_sel_hi:[1,0]
	s_nop 0
	v_div_scale_f32 v138, s[46:47], v213, v213, 1.0
	v_rcp_f32_e32 v165, v138
	s_nop 0
	v_fma_f32 v167, -v138, v165, 1.0
	v_fmac_f32_e32 v165, v167, v165
	v_div_scale_f32 v167, vcc, 1.0, v213, 1.0
	v_mul_f32_e32 v201, v167, v165
	v_fma_f32 v229, -v138, v201, v167
	v_fmac_f32_e32 v201, v229, v165
	v_fma_f32 v138, -v138, v201, v167
	v_div_fmas_f32 v138, v138, v165, v201
	v_div_fixup_f32 v213, v138, v213, 1.0
	v_div_scale_f32 v138, s[46:47], v212, v212, 1.0
	v_rcp_f32_e32 v165, v138
	s_nop 0
	v_fma_f32 v167, -v138, v165, 1.0
	v_fmac_f32_e32 v165, v167, v165
	v_div_scale_f32 v167, vcc, 1.0, v212, 1.0
	v_mul_f32_e32 v201, v167, v165
	v_fma_f32 v229, -v138, v201, v167
	v_fmac_f32_e32 v201, v229, v165
	v_fma_f32 v138, -v138, v201, v167
	v_div_fmas_f32 v138, v138, v165, v201
	v_div_fixup_f32 v212, v138, v212, 1.0
	v_pk_mul_f32 v[212:213], v[212:213], v[136:137]
	v_lshlrev_b32_e32 v136, 16, v139
	v_and_b32_e32 v137, 0xffff0000, v139
	v_pk_mul_f32 v[136:137], v[148:149], v[136:137] op_sel_hi:[0,1]
	v_pk_mul_f32 v[138:139], v[58:59], v[200:201] op_sel_hi:[1,0]
; DI unsigned pk(float lo, float hi) { f32x2 v = {lo, hi}; bf2_t b = __builtin_convertvector(v, bf2_t); return __builtin_bit_cast(unsigned, b); }
; DI float bflo(unsigned w) { return __uint_as_float(w << 16); }
; DI float bfhi(unsigned w) { return __uint_as_float(w & 0xffff0000u); }
; DI float sigmoidf_(float x) { return 1.0f / (1.0f + __expf(-x)); }
; DI void gemm_epilogue(const GemmDesc& g, f32x4 (&acc)[2][2][4][2], int brow, int bcol, int wr, int wc, int fr, int fq) {
;     ...
;           const int row = rowb + ai * HALF + m * 16;
;           float rs;
;           { const float* sp = g.f0 + (size_t)row * 32 + head * 8;
;             const f32x4 s0 = gld<f32x4>(sp); float ssum = (s0[0] + s0[1]) + (s0[2] + s0[3]);
;             if (g.dvshift == 9) { const f32x4 s1 = gld<f32x4>(sp + 4); ssum += (s1[0] + s1[1]) + (s1[2] + s1[3]); }
;             rs = rsqrtf(ssum * (g.dvshift == 9 ? (1.0f / 512.0f) : (1.0f / 256.0f)) + EPS); }
;           bf16_t* op = g.o0 + (size_t)row * N + col;
;           const u32x4 ow = gld<u32x4>(op);
;           const float ru = gld<float>(g.rowscale + row);
;           const f32x4 v0 = acc[ai][bj][m][0] * ru, v1 = acc[ai][bj][m][1] * ru;
;           float o[8] = {bflo(ow.x), bfhi(ow.x), bflo(ow.y), bfhi(ow.y), bflo(ow.z), bfhi(ow.z), bflo(ow.w), bfhi(ow.w)};
; #pragma unroll
;           for (int j = 0; j < 4; ++j) { o[j] = o[j] * rs * g0[j] * v0[j] * sigmoidf_(v0[j]); o[4 + j] = o[4 + j] * rs * g1[j] * v1[j] * sigmoidf_(v1[j]); }
;           u32x4 w; w.x = pk(o[0], o[1]); w.y = pk(o[2], o[3]); w.z = pk(o[4], o[5]); w.w = pk(o[6], o[7]);
;           gst<u32x4>(op, w);
	v_pk_mul_f32 v[136:137], v[130:131], v[136:137]
	v_mul_f32_e32 v165, 0xbfb8aa3b, v138
	v_pk_mul_f32 v[136:137], v[138:139], v[136:137]
	v_mul_f32_e32 v138, 0xbfb8aa3b, v139
	v_exp_f32_e32 v200, v165
	v_exp_f32_e32 v201, v138
	s_nop 0
	v_pk_add_f32 v[138:139], v[200:201], 1.0 op_sel_hi:[1,0]
	s_nop 0
	v_div_scale_f32 v148, s[46:47], v139, v139, 1.0
	v_rcp_f32_e32 v165, v148
	s_nop 0
	v_fma_f32 v167, -v148, v165, 1.0
	v_fmac_f32_e32 v165, v167, v165
	v_div_scale_f32 v167, vcc, 1.0, v139, 1.0
	v_mul_f32_e32 v200, v167, v165
	v_fma_f32 v201, -v148, v200, v167
	v_fmac_f32_e32 v200, v201, v165
	v_fma_f32 v148, -v148, v200, v167
	v_div_fmas_f32 v148, v148, v165, v200
	v_div_fixup_f32 v139, v148, v139, 1.0
	v_div_scale_f32 v148, s[46:47], v138, v138, 1.0
	v_rcp_f32_e32 v165, v148
	s_nop 0
	v_fma_f32 v167, -v148, v165, 1.0
	v_fmac_f32_e32 v165, v167, v165
	v_div_scale_f32 v167, vcc, 1.0, v138, 1.0
	v_mul_f32_e32 v200, v167, v165
	v_fma_f32 v201, -v148, v200, v167
	v_fmac_f32_e32 v200, v201, v165
	v_fma_f32 v148, -v148, v200, v167
	v_div_fmas_f32 v148, v148, v165, v200
	v_div_fixup_f32 v138, v148, v138, 1.0
	v_pk_mul_f32 v[200:201], v[138:139], v[136:137]
	v_cvt_pk_bf16_f32 v136, v182, v183
	v_cvt_pk_bf16_f32 v137, v212, v213
	v_cvt_pk_bf16_f32 v138, v202, v203
	v_cvt_pk_bf16_f32 v139, v200, v201
	global_store_dwordx4 v[142:143], v[136:139], off offset:256
	s_and_b64 vcc, exec, s[44:45]
	s_nop 0
	v_lshl_add_u64 v[138:139], v[198:199], 2, v[184:185]
	global_load_dwordx4 v[182:185], v[138:139], off
	global_load_dwordx4 v[232:235], v[138:139], off offset:16
	s_waitcnt vmcnt(0)
	v_mov_b32_e32 v136, v183
	v_mov_b32_e32 v137, v184
	v_mov_b32_e32 v183, v185
	v_pk_add_f32 v[136:137], v[136:137], v[182:183]
	s_nop 0
	v_pk_add_f32 v[136:137], v[136:137], v[136:137] op_sel:[0,1] op_sel_hi:[1,0]
	s_cbranch_vccnz .LBB0_242
	v_mov_b64_e32 v[182:183], v[232:233]
	v_mov_b64_e32 v[184:185], v[234:235]
	s_mov_b32 s26, 0x3b000000
	v_mov_b32_e32 v138, v183
	v_mov_b32_e32 v139, v184
	v_mov_b32_e32 v183, v185
	v_pk_add_f32 v[138:139], v[138:139], v[182:183]
	s_nop 0
	v_add_f32_e32 v137, v138, v139
	v_add_f32_e32 v136, v136, v137
.LBB0_242:
	v_fma_f32 v136, s26, v136, v204
	v_cmp_gt_f32_e32 vcc, s33, v136
	v_mul_f32_e32 v137, 0x4b800000, v136
	s_nop 0
	v_cndmask_b32_e32 v136, v136, v137, vcc
	v_rsq_f32_e32 v136, v136
	s_nop 0
	v_mul_f32_e32 v137, 0x45800000, v136
	v_cndmask_b32_e32 v142, v136, v137, vcc
	global_load_dwordx4 v[136:139], v[168:169], off offset:256
	global_load_dword v148, v[140:141], off offset:64
	s_waitcnt vmcnt(1)
	v_lshlrev_b32_e32 v182, 16, v136
	s_waitcnt vmcnt(0)
	v_pk_mul_f32 v[184:185], v[52:53], v[148:149] op_sel_hi:[1,0]
	v_and_b32_e32 v183, 0xffff0000, v136
	v_mul_f32_e32 v136, 0xbfb8aa3b, v184
	v_exp_f32_e32 v200, v136
	v_mul_f32_e32 v136, 0xbfb8aa3b, v185
	v_exp_f32_e32 v201, v136
	v_pk_mul_f32 v[182:183], v[142:143], v[182:183] op_sel_hi:[0,1]
	v_pk_mul_f32 v[182:183], v[132:133], v[182:183]
	s_nop 0
	v_pk_mul_f32 v[182:183], v[184:185], v[182:183]
	v_pk_add_f32 v[184:185], v[200:201], 1.0 op_sel_hi:[1,0]
	s_nop 0
	v_div_scale_f32 v136, s[26:27], v185, v185, 1.0
	v_rcp_f32_e32 v143, v136
	s_nop 0
	v_fma_f32 v165, -v136, v143, 1.0
	v_fmac_f32_e32 v143, v165, v143
	v_div_scale_f32 v165, vcc, 1.0, v185, 1.0
	v_mul_f32_e32 v167, v165, v143
	v_fma_f32 v200, -v136, v167, v165
	v_fmac_f32_e32 v167, v200, v143
	v_fma_f32 v136, -v136, v167, v165
	v_div_fmas_f32 v136, v136, v143, v167
	v_div_fixup_f32 v185, v136, v185, 1.0
	v_div_scale_f32 v136, s[26:27], v184, v184, 1.0
	v_rcp_f32_e32 v143, v136
	s_nop 0
	v_fma_f32 v165, -v136, v143, 1.0
	v_fmac_f32_e32 v143, v165, v143
	v_div_scale_f32 v165, vcc, 1.0, v184, 1.0
	v_mul_f32_e32 v167, v165, v143
	v_fma_f32 v200, -v136, v167, v165
	v_fmac_f32_e32 v167, v200, v143
	v_fma_f32 v136, -v136, v167, v165
	v_div_fmas_f32 v136, v136, v143, v167
	v_pk_mul_f32 v[200:201], v[48:49], v[148:149] op_sel_hi:[1,0]
	v_div_fixup_f32 v184, v136, v184, 1.0
	v_mul_f32_e32 v136, 0xbfb8aa3b, v200
	v_exp_f32_e32 v202, v136
	v_mul_f32_e32 v136, 0xbfb8aa3b, v201
	v_exp_f32_e32 v203, v136
	v_pk_mul_f32 v[182:183], v[184:185], v[182:183]
	v_lshlrev_b32_e32 v184, 16, v138
	v_and_b32_e32 v185, 0xffff0000, v138
	v_pk_mul_f32 v[184:185], v[142:143], v[184:185] op_sel_hi:[0,1]
	v_pk_mul_f32 v[184:185], v[128:129], v[184:185]
	s_nop 0
	v_pk_mul_f32 v[184:185], v[200:201], v[184:185]
	v_pk_add_f32 v[200:201], v[202:203], 1.0 op_sel_hi:[1,0]
	s_nop 0
	v_div_scale_f32 v136, s[26:27], v201, v201, 1.0
	v_rcp_f32_e32 v138, v136
	s_nop 0
	v_fma_f32 v143, -v136, v138, 1.0
	v_fmac_f32_e32 v138, v143, v138
	v_div_scale_f32 v143, vcc, 1.0, v201, 1.0
	v_mul_f32_e32 v165, v143, v138
	v_fma_f32 v167, -v136, v165, v143
	v_fmac_f32_e32 v165, v167, v138
	v_fma_f32 v136, -v136, v165, v143
	v_div_fmas_f32 v136, v136, v138, v165
	v_div_fixup_f32 v201, v136, v201, 1.0
	v_div_scale_f32 v136, s[26:27], v200, v200, 1.0
	v_rcp_f32_e32 v138, v136
	s_nop 0
	v_fma_f32 v143, -v136, v138, 1.0
	v_fmac_f32_e32 v138, v143, v138
	v_div_scale_f32 v143, vcc, 1.0, v200, 1.0
	v_mul_f32_e32 v165, v143, v138
	v_fma_f32 v167, -v136, v165, v143
	v_fmac_f32_e32 v165, v167, v138
	v_fma_f32 v136, -v136, v165, v143
	v_div_fmas_f32 v136, v136, v138, v165
	v_div_fixup_f32 v200, v136, v200, 1.0
	v_pk_mul_f32 v[184:185], v[200:201], v[184:185]
	v_pk_mul_f32 v[200:201], v[54:55], v[148:149] op_sel_hi:[1,0]
	v_lshlrev_b32_e32 v136, 16, v137
	v_mul_f32_e32 v138, 0xbfb8aa3b, v200
	v_exp_f32_e32 v202, v138
	v_mul_f32_e32 v138, 0xbfb8aa3b, v201
	v_exp_f32_e32 v203, v138
	v_and_b32_e32 v137, 0xffff0000, v137
	v_pk_mul_f32 v[136:137], v[142:143], v[136:137] op_sel_hi:[0,1]
; DI unsigned pk(float lo, float hi) { f32x2 v = {lo, hi}; bf2_t b = __builtin_convertvector(v, bf2_t); return __builtin_bit_cast(unsigned, b); }
; DI float bflo(unsigned w) { return __uint_as_float(w << 16); }
; DI float bfhi(unsigned w) { return __uint_as_float(w & 0xffff0000u); }
; DI float sigmoidf_(float x) { return 1.0f / (1.0f + __expf(-x)); }
; DI void gemm_epilogue(const GemmDesc& g, f32x4 (&acc)[2][2][4][2], int brow, int bcol, int wr, int wc, int fr, int fq) {
;     ...
;           const int row = rowb + ai * HALF + m * 16;
;           float rs;
;           { const float* sp = g.f0 + (size_t)row * 32 + head * 8;
;             const f32x4 s0 = gld<f32x4>(sp); float ssum = (s0[0] + s0[1]) + (s0[2] + s0[3]);
;             if (g.dvshift == 9) { const f32x4 s1 = gld<f32x4>(sp + 4); ssum += (s1[0] + s1[1]) + (s1[2] + s1[3]); }
;             rs = rsqrtf(ssum * (g.dvshift == 9 ? (1.0f / 512.0f) : (1.0f / 256.0f)) + EPS); }
;           bf16_t* op = g.o0 + (size_t)row * N + col;
;           const u32x4 ow = gld<u32x4>(op);
;           const float ru = gld<float>(g.rowscale + row);
;           const f32x4 v0 = acc[ai][bj][m][0] * ru, v1 = acc[ai][bj][m][1] * ru;
;           float o[8] = {bflo(ow.x), bfhi(ow.x), bflo(ow.y), bfhi(ow.y), bflo(ow.z), bfhi(ow.z), bflo(ow.w), bfhi(ow.w)};
; #pragma unroll
;           for (int j = 0; j < 4; ++j) { o[j] = o[j] * rs * g0[j] * v0[j] * sigmoidf_(v0[j]); o[4 + j] = o[4 + j] * rs * g1[j] * v1[j] * sigmoidf_(v1[j]); }
;           u32x4 w; w.x = pk(o[0], o[1]); w.y = pk(o[2], o[3]); w.z = pk(o[4], o[5]); w.w = pk(o[6], o[7]);
;           gst<u32x4>(op, w);
	v_pk_mul_f32 v[136:137], v[134:135], v[136:137]
	s_nop 0
	v_pk_mul_f32 v[136:137], v[200:201], v[136:137]
	v_pk_add_f32 v[200:201], v[202:203], 1.0 op_sel_hi:[1,0]
	s_nop 0
	v_div_scale_f32 v138, s[26:27], v201, v201, 1.0
	v_rcp_f32_e32 v143, v138
	s_nop 0
	v_fma_f32 v165, -v138, v143, 1.0
	v_fmac_f32_e32 v143, v165, v143
	v_div_scale_f32 v165, vcc, 1.0, v201, 1.0
	v_mul_f32_e32 v167, v165, v143
	v_fma_f32 v202, -v138, v167, v165
	v_fmac_f32_e32 v167, v202, v143
	v_fma_f32 v138, -v138, v167, v165
	v_div_fmas_f32 v138, v138, v143, v167
	v_div_fixup_f32 v201, v138, v201, 1.0
	v_div_scale_f32 v138, s[26:27], v200, v200, 1.0
	v_rcp_f32_e32 v143, v138
	s_nop 0
	v_fma_f32 v165, -v138, v143, 1.0
	v_fmac_f32_e32 v143, v165, v143
	v_div_scale_f32 v165, vcc, 1.0, v200, 1.0
	v_mul_f32_e32 v167, v165, v143
	v_fma_f32 v202, -v138, v167, v165
	v_fmac_f32_e32 v167, v202, v143
	v_fma_f32 v138, -v138, v167, v165
	v_div_fmas_f32 v138, v138, v143, v167
	v_div_fixup_f32 v200, v138, v200, 1.0
	v_pk_mul_f32 v[200:201], v[200:201], v[136:137]
	v_lshlrev_b32_e32 v136, 16, v139
	v_and_b32_e32 v137, 0xffff0000, v139
	v_pk_mul_f32 v[138:139], v[50:51], v[148:149] op_sel_hi:[1,0]
	s_nop 0
	v_mul_f32_e32 v143, 0xbfb8aa3b, v138
	v_pk_mul_f32 v[136:137], v[142:143], v[136:137] op_sel_hi:[0,1]
	v_pk_mul_f32 v[136:137], v[130:131], v[136:137]
	v_exp_f32_e32 v202, v143
	v_pk_mul_f32 v[136:137], v[138:139], v[136:137]
	v_mul_f32_e32 v138, 0xbfb8aa3b, v139
	v_exp_f32_e32 v203, v138
	s_nop 0
	v_pk_add_f32 v[138:139], v[202:203], 1.0 op_sel_hi:[1,0]
	s_nop 0
	v_div_scale_f32 v142, s[26:27], v139, v139, 1.0
	v_rcp_f32_e32 v143, v142
	s_nop 0
	v_fma_f32 v148, -v142, v143, 1.0
	v_fmac_f32_e32 v143, v148, v143
	v_div_scale_f32 v148, vcc, 1.0, v139, 1.0
	v_mul_f32_e32 v165, v148, v143
	v_fma_f32 v167, -v142, v165, v148
	v_fmac_f32_e32 v165, v167, v143
	v_fma_f32 v142, -v142, v165, v148
	v_div_fmas_f32 v142, v142, v143, v165
	v_div_fixup_f32 v139, v142, v139, 1.0
	v_div_scale_f32 v142, s[26:27], v138, v138, 1.0
	v_rcp_f32_e32 v143, v142
	s_mov_b32 s26, 0x3b800000
	s_mov_b32 s27, 0x3b800000
	v_fma_f32 v148, -v142, v143, 1.0
	v_fmac_f32_e32 v143, v148, v143
	v_div_scale_f32 v148, vcc, 1.0, v138, 1.0
	v_mul_f32_e32 v165, v148, v143
	v_fma_f32 v167, -v142, v165, v148
	v_fmac_f32_e32 v165, v167, v143
	v_fma_f32 v142, -v142, v165, v148
	v_div_fmas_f32 v142, v142, v143, v165
	v_div_fixup_f32 v138, v142, v138, 1.0
	v_pk_mul_f32 v[142:143], v[138:139], v[136:137]
	v_cvt_pk_bf16_f32 v136, v182, v183
	v_cvt_pk_bf16_f32 v137, v200, v201
	v_cvt_pk_bf16_f32 v138, v184, v185
	v_cvt_pk_bf16_f32 v139, v142, v143
	global_store_dwordx4 v[168:169], v[136:139], off offset:256
	s_and_b64 vcc, exec, s[44:45]
	s_nop 0
	v_lshl_add_u64 v[138:139], v[198:199], 2, v[186:187]
	global_load_dwordx4 v[182:185], v[138:139], off
	global_load_dwordx4 v[232:235], v[138:139], off offset:16
	s_waitcnt vmcnt(0)
	v_mov_b32_e32 v136, v183
	v_mov_b32_e32 v137, v184
	v_mov_b32_e32 v183, v185
	v_pk_add_f32 v[136:137], v[136:137], v[182:183]
	s_nop 0
	v_pk_add_f32 v[136:137], v[136:137], v[136:137] op_sel:[0,1] op_sel_hi:[1,0]
	s_cbranch_vccnz .LBB0_244
	v_mov_b64_e32 v[182:183], v[232:233]
	v_mov_b64_e32 v[184:185], v[234:235]
	s_mov_b32 s27, 0x3b000000
	v_mov_b32_e32 v138, v183
	v_mov_b32_e32 v139, v184
	v_mov_b32_e32 v183, v185
	v_pk_add_f32 v[138:139], v[138:139], v[182:183]
	s_nop 0
	v_add_f32_e32 v137, v138, v139
	v_add_f32_e32 v136, v136, v137
.LBB0_244:
	v_fma_f32 v136, s27, v136, v204
	v_cmp_gt_f32_e32 vcc, s33, v136
	v_mul_f32_e32 v137, 0x4b800000, v136
	s_nop 0
	v_cndmask_b32_e32 v136, v136, v137, vcc
	v_rsq_f32_e32 v136, v136
	s_nop 0
	v_mul_f32_e32 v137, 0x45800000, v136
	v_cndmask_b32_e32 v142, v136, v137, vcc
	global_load_dwordx4 v[136:139], v[170:171], off offset:256
	global_load_dword v148, v[140:141], off offset:128
	s_waitcnt vmcnt(1)
	v_lshlrev_b32_e32 v168, 16, v136
	s_waitcnt vmcnt(0)
	v_pk_mul_f32 v[182:183], v[44:45], v[148:149] op_sel_hi:[1,0]
	v_and_b32_e32 v169, 0xffff0000, v136
	v_mul_f32_e32 v136, 0xbfb8aa3b, v182
	v_exp_f32_e32 v184, v136
	v_mul_f32_e32 v136, 0xbfb8aa3b, v183
	v_exp_f32_e32 v185, v136
	v_pk_mul_f32 v[168:169], v[142:143], v[168:169] op_sel_hi:[0,1]
	v_pk_mul_f32 v[168:169], v[132:133], v[168:169]
	s_nop 0
	v_pk_mul_f32 v[168:169], v[182:183], v[168:169]
	v_pk_add_f32 v[182:183], v[184:185], 1.0 op_sel_hi:[1,0]
	s_nop 0
	v_div_scale_f32 v136, s[46:47], v183, v183, 1.0
	v_rcp_f32_e32 v143, v136
	s_nop 0
	v_fma_f32 v165, -v136, v143, 1.0
	v_fmac_f32_e32 v143, v165, v143
	v_div_scale_f32 v165, vcc, 1.0, v183, 1.0
	v_mul_f32_e32 v167, v165, v143
	v_fma_f32 v184, -v136, v167, v165
	v_fmac_f32_e32 v167, v184, v143
	v_fma_f32 v136, -v136, v167, v165
	v_div_fmas_f32 v136, v136, v143, v167
	v_div_fixup_f32 v183, v136, v183, 1.0
	v_div_scale_f32 v136, s[46:47], v182, v182, 1.0
	v_rcp_f32_e32 v143, v136
	s_nop 0
	v_fma_f32 v165, -v136, v143, 1.0
	v_fmac_f32_e32 v143, v165, v143
	v_div_scale_f32 v165, vcc, 1.0, v182, 1.0
	v_mul_f32_e32 v167, v165, v143
	v_fma_f32 v184, -v136, v167, v165
	v_fmac_f32_e32 v167, v184, v143
	v_fma_f32 v136, -v136, v167, v165
	v_div_fmas_f32 v136, v136, v143, v167
	v_pk_mul_f32 v[184:185], v[40:41], v[148:149] op_sel_hi:[1,0]
	v_div_fixup_f32 v182, v136, v182, 1.0
	v_mul_f32_e32 v136, 0xbfb8aa3b, v184
	v_exp_f32_e32 v186, v136
	v_mul_f32_e32 v136, 0xbfb8aa3b, v185
	v_exp_f32_e32 v187, v136
	v_pk_mul_f32 v[168:169], v[182:183], v[168:169]
	v_lshlrev_b32_e32 v182, 16, v138
	v_and_b32_e32 v183, 0xffff0000, v138
	v_pk_mul_f32 v[182:183], v[142:143], v[182:183] op_sel_hi:[0,1]
	v_pk_mul_f32 v[182:183], v[128:129], v[182:183]
	s_nop 0
	v_pk_mul_f32 v[182:183], v[184:185], v[182:183]
; DI unsigned pk(float lo, float hi) { f32x2 v = {lo, hi}; bf2_t b = __builtin_convertvector(v, bf2_t); return __builtin_bit_cast(unsigned, b); }
; DI float bflo(unsigned w) { return __uint_as_float(w << 16); }
; DI float bfhi(unsigned w) { return __uint_as_float(w & 0xffff0000u); }
; DI float sigmoidf_(float x) { return 1.0f / (1.0f + __expf(-x)); }
; DI void gemm_epilogue(const GemmDesc& g, f32x4 (&acc)[2][2][4][2], int brow, int bcol, int wr, int wc, int fr, int fq) {
;     ...
;           const int row = rowb + ai * HALF + m * 16;
;           float rs;
;           { const float* sp = g.f0 + (size_t)row * 32 + head * 8;
;             const f32x4 s0 = gld<f32x4>(sp); float ssum = (s0[0] + s0[1]) + (s0[2] + s0[3]);
;             if (g.dvshift == 9) { const f32x4 s1 = gld<f32x4>(sp + 4); ssum += (s1[0] + s1[1]) + (s1[2] + s1[3]); }
;             rs = rsqrtf(ssum * (g.dvshift == 9 ? (1.0f / 512.0f) : (1.0f / 256.0f)) + EPS); }
;           bf16_t* op = g.o0 + (size_t)row * N + col;
;           const u32x4 ow = gld<u32x4>(op);
;           const float ru = gld<float>(g.rowscale + row);
;           const f32x4 v0 = acc[ai][bj][m][0] * ru, v1 = acc[ai][bj][m][1] * ru;
;           float o[8] = {bflo(ow.x), bfhi(ow.x), bflo(ow.y), bfhi(ow.y), bflo(ow.z), bfhi(ow.z), bflo(ow.w), bfhi(ow.w)};
; #pragma unroll
;           for (int j = 0; j < 4; ++j) { o[j] = o[j] * rs * g0[j] * v0[j] * sigmoidf_(v0[j]); o[4 + j] = o[4 + j] * rs * g1[j] * v1[j] * sigmoidf_(v1[j]); }
;           u32x4 w; w.x = pk(o[0], o[1]); w.y = pk(o[2], o[3]); w.z = pk(o[4], o[5]); w.w = pk(o[6], o[7]);
;           gst<u32x4>(op, w);
	v_pk_add_f32 v[184:185], v[186:187], 1.0 op_sel_hi:[1,0]
	s_nop 0
	v_div_scale_f32 v136, s[46:47], v185, v185, 1.0
	v_rcp_f32_e32 v138, v136
	s_nop 0
	v_fma_f32 v143, -v136, v138, 1.0
	v_fmac_f32_e32 v138, v143, v138
	v_div_scale_f32 v143, vcc, 1.0, v185, 1.0
	v_mul_f32_e32 v165, v143, v138
	v_fma_f32 v167, -v136, v165, v143
	v_fmac_f32_e32 v165, v167, v138
	v_fma_f32 v136, -v136, v165, v143
	v_div_fmas_f32 v136, v136, v138, v165
	v_div_fixup_f32 v185, v136, v185, 1.0
	v_div_scale_f32 v136, s[46:47], v184, v184, 1.0
	v_rcp_f32_e32 v138, v136
	s_nop 0
	v_fma_f32 v143, -v136, v138, 1.0
	v_fmac_f32_e32 v138, v143, v138
	v_div_scale_f32 v143, vcc, 1.0, v184, 1.0
	v_mul_f32_e32 v165, v143, v138
	v_fma_f32 v167, -v136, v165, v143
	v_fmac_f32_e32 v165, v167, v138
	v_fma_f32 v136, -v136, v165, v143
	v_div_fmas_f32 v136, v136, v138, v165
	v_div_fixup_f32 v184, v136, v184, 1.0
	v_pk_mul_f32 v[182:183], v[184:185], v[182:183]
	v_pk_mul_f32 v[184:185], v[46:47], v[148:149] op_sel_hi:[1,0]
	v_lshlrev_b32_e32 v136, 16, v137
	v_mul_f32_e32 v138, 0xbfb8aa3b, v184
	v_exp_f32_e32 v186, v138
	v_mul_f32_e32 v138, 0xbfb8aa3b, v185
	v_exp_f32_e32 v187, v138
	v_and_b32_e32 v137, 0xffff0000, v137
	v_pk_mul_f32 v[136:137], v[142:143], v[136:137] op_sel_hi:[0,1]
	v_pk_mul_f32 v[136:137], v[134:135], v[136:137]
	s_nop 0
	v_pk_mul_f32 v[136:137], v[184:185], v[136:137]
	v_pk_add_f32 v[184:185], v[186:187], 1.0 op_sel_hi:[1,0]
	s_nop 0
	v_div_scale_f32 v138, s[46:47], v185, v185, 1.0
	v_rcp_f32_e32 v143, v138
	s_nop 0
	v_fma_f32 v165, -v138, v143, 1.0
	v_fmac_f32_e32 v143, v165, v143
	v_div_scale_f32 v165, vcc, 1.0, v185, 1.0
	v_mul_f32_e32 v167, v165, v143
	v_fma_f32 v186, -v138, v167, v165
	v_fmac_f32_e32 v167, v186, v143
	v_fma_f32 v138, -v138, v167, v165
	v_div_fmas_f32 v138, v138, v143, v167
	v_div_fixup_f32 v185, v138, v185, 1.0
	v_div_scale_f32 v138, s[46:47], v184, v184, 1.0
	v_rcp_f32_e32 v143, v138
	s_nop 0
	v_fma_f32 v165, -v138, v143, 1.0
	v_fmac_f32_e32 v143, v165, v143
	v_div_scale_f32 v165, vcc, 1.0, v184, 1.0
	v_mul_f32_e32 v167, v165, v143
	v_fma_f32 v186, -v138, v167, v165
	v_fmac_f32_e32 v167, v186, v143
	v_fma_f32 v138, -v138, v167, v165
	v_div_fmas_f32 v138, v138, v143, v167
	v_div_fixup_f32 v184, v138, v184, 1.0
	v_pk_mul_f32 v[184:185], v[184:185], v[136:137]
	v_lshlrev_b32_e32 v136, 16, v139
	v_and_b32_e32 v137, 0xffff0000, v139
	v_pk_mul_f32 v[138:139], v[42:43], v[148:149] op_sel_hi:[1,0]
	s_nop 0
	v_mul_f32_e32 v143, 0xbfb8aa3b, v138
	v_pk_mul_f32 v[136:137], v[142:143], v[136:137] op_sel_hi:[0,1]
	v_pk_mul_f32 v[136:137], v[130:131], v[136:137]
	v_exp_f32_e32 v186, v143
	v_pk_mul_f32 v[136:137], v[138:139], v[136:137]
	v_mul_f32_e32 v138, 0xbfb8aa3b, v139
	v_exp_f32_e32 v187, v138
	s_nop 0
	v_pk_add_f32 v[138:139], v[186:187], 1.0 op_sel_hi:[1,0]
	s_nop 0
	v_div_scale_f32 v142, s[46:47], v139, v139, 1.0
	v_rcp_f32_e32 v143, v142
	s_nop 0
	v_fma_f32 v148, -v142, v143, 1.0
	v_fmac_f32_e32 v143, v148, v143
	v_div_scale_f32 v148, vcc, 1.0, v139, 1.0
	v_mul_f32_e32 v165, v148, v143
	v_fma_f32 v167, -v142, v165, v148
	v_fmac_f32_e32 v165, v167, v143
	v_fma_f32 v142, -v142, v165, v148
	v_div_fmas_f32 v142, v142, v143, v165
	v_div_fixup_f32 v139, v142, v139, 1.0
	v_div_scale_f32 v142, s[46:47], v138, v138, 1.0
	v_rcp_f32_e32 v143, v142
	s_nop 0
	v_fma_f32 v148, -v142, v143, 1.0
	v_fmac_f32_e32 v143, v148, v143
	v_div_scale_f32 v148, vcc, 1.0, v138, 1.0
	v_mul_f32_e32 v165, v148, v143
	v_fma_f32 v167, -v142, v165, v148
	v_fmac_f32_e32 v165, v167, v143
	v_fma_f32 v142, -v142, v165, v148
	v_div_fmas_f32 v142, v142, v143, v165
	v_div_fixup_f32 v138, v142, v138, 1.0
	v_pk_mul_f32 v[142:143], v[138:139], v[136:137]
	v_cvt_pk_bf16_f32 v136, v168, v169
	v_cvt_pk_bf16_f32 v137, v184, v185
	v_cvt_pk_bf16_f32 v138, v182, v183
	v_cvt_pk_bf16_f32 v139, v142, v143
	global_store_dwordx4 v[170:171], v[136:139], off offset:256
	s_and_b64 vcc, exec, s[44:45]
	s_nop 0
	v_lshl_add_u64 v[138:139], v[198:199], 2, v[188:189]
	global_load_dwordx4 v[168:171], v[138:139], off
	global_load_dwordx4 v[232:235], v[138:139], off offset:16
	s_waitcnt vmcnt(0)
	v_mov_b32_e32 v136, v169
	v_mov_b32_e32 v137, v170
	v_mov_b32_e32 v169, v171
	v_pk_add_f32 v[136:137], v[136:137], v[168:169]
	s_nop 0
	v_pk_add_f32 v[136:137], v[136:137], v[136:137] op_sel:[0,1] op_sel_hi:[1,0]
	s_cbranch_vccnz .LBB0_246
	v_mov_b64_e32 v[168:169], v[232:233]
	v_mov_b64_e32 v[170:171], v[234:235]
	s_mov_b32 s26, 0x3b000000
	v_mov_b32_e32 v138, v169
	v_mov_b32_e32 v139, v170
	v_mov_b32_e32 v169, v171
	v_pk_add_f32 v[138:139], v[138:139], v[168:169]
	s_nop 0
	v_add_f32_e32 v137, v138, v139
	v_add_f32_e32 v136, v136, v137
; DI unsigned pk(float lo, float hi) { f32x2 v = {lo, hi}; bf2_t b = __builtin_convertvector(v, bf2_t); return __builtin_bit_cast(unsigned, b); }
; DI float bflo(unsigned w) { return __uint_as_float(w << 16); }
; DI float bfhi(unsigned w) { return __uint_as_float(w & 0xffff0000u); }
; DI float sigmoidf_(float x) { return 1.0f / (1.0f + __expf(-x)); }
; DI void gemm_epilogue(const GemmDesc& g, f32x4 (&acc)[2][2][4][2], int brow, int bcol, int wr, int wc, int fr, int fq) {
;     ...
;           const int row = rowb + ai * HALF + m * 16;
;           float rs;
;           { const float* sp = g.f0 + (size_t)row * 32 + head * 8;
;             const f32x4 s0 = gld<f32x4>(sp); float ssum = (s0[0] + s0[1]) + (s0[2] + s0[3]);
;             if (g.dvshift == 9) { const f32x4 s1 = gld<f32x4>(sp + 4); ssum += (s1[0] + s1[1]) + (s1[2] + s1[3]); }
;             rs = rsqrtf(ssum * (g.dvshift == 9 ? (1.0f / 512.0f) : (1.0f / 256.0f)) + EPS); }
;           bf16_t* op = g.o0 + (size_t)row * N + col;
;           const u32x4 ow = gld<u32x4>(op);
;           const float ru = gld<float>(g.rowscale + row);
;           const f32x4 v0 = acc[ai][bj][m][0] * ru, v1 = acc[ai][bj][m][1] * ru;
;           float o[8] = {bflo(ow.x), bfhi(ow.x), bflo(ow.y), bfhi(ow.y), bflo(ow.z), bfhi(ow.z), bflo(ow.w), bfhi(ow.w)};
; #pragma unroll
;           for (int j = 0; j < 4; ++j) { o[j] = o[j] * rs * g0[j] * v0[j] * sigmoidf_(v0[j]); o[4 + j] = o[4 + j] * rs * g1[j] * v1[j] * sigmoidf_(v1[j]); }
;           u32x4 w; w.x = pk(o[0], o[1]); w.y = pk(o[2], o[3]); w.z = pk(o[4], o[5]); w.w = pk(o[6], o[7]);
;           gst<u32x4>(op, w);
.LBB0_246:
	v_fma_f32 v136, s26, v136, v204
	v_cmp_gt_f32_e32 vcc, s33, v136
	v_mul_f32_e32 v137, 0x4b800000, v136
	s_nop 0
	v_cndmask_b32_e32 v136, v136, v137, vcc
	v_rsq_f32_e32 v136, v136
	s_nop 0
	v_mul_f32_e32 v137, 0x45800000, v136
	v_cndmask_b32_e32 v142, v136, v137, vcc
	global_load_dwordx4 v[136:139], v[172:173], off offset:256
	global_load_dword v148, v[140:141], off offset:192
	s_waitcnt vmcnt(1)
	v_lshlrev_b32_e32 v168, 16, v136
	s_waitcnt vmcnt(0)
	v_pk_mul_f32 v[170:171], v[36:37], v[148:149] op_sel_hi:[1,0]
	v_and_b32_e32 v169, 0xffff0000, v136
	v_mul_f32_e32 v136, 0xbfb8aa3b, v170
	v_exp_f32_e32 v182, v136
	v_mul_f32_e32 v136, 0xbfb8aa3b, v171
	v_exp_f32_e32 v183, v136
	v_pk_mul_f32 v[168:169], v[142:143], v[168:169] op_sel_hi:[0,1]
	v_pk_mul_f32 v[168:169], v[132:133], v[168:169]
	s_nop 0
	v_pk_mul_f32 v[168:169], v[170:171], v[168:169]
	v_pk_add_f32 v[170:171], v[182:183], 1.0 op_sel_hi:[1,0]
	s_nop 0
	v_div_scale_f32 v136, s[26:27], v171, v171, 1.0
	v_rcp_f32_e32 v143, v136
	s_nop 0
	v_fma_f32 v165, -v136, v143, 1.0
	v_fmac_f32_e32 v143, v165, v143
	v_div_scale_f32 v165, vcc, 1.0, v171, 1.0
	v_mul_f32_e32 v167, v165, v143
	v_fma_f32 v182, -v136, v167, v165
	v_fmac_f32_e32 v167, v182, v143
	v_fma_f32 v136, -v136, v167, v165
	v_div_fmas_f32 v136, v136, v143, v167
	v_div_fixup_f32 v171, v136, v171, 1.0
	v_div_scale_f32 v136, s[26:27], v170, v170, 1.0
	v_rcp_f32_e32 v143, v136
	s_nop 0
	v_fma_f32 v165, -v136, v143, 1.0
	v_fmac_f32_e32 v143, v165, v143
	v_div_scale_f32 v165, vcc, 1.0, v170, 1.0
	v_mul_f32_e32 v167, v165, v143
	v_fma_f32 v182, -v136, v167, v165
	v_fmac_f32_e32 v167, v182, v143
	v_fma_f32 v136, -v136, v167, v165
	v_div_fmas_f32 v136, v136, v143, v167
	v_pk_mul_f32 v[182:183], v[32:33], v[148:149] op_sel_hi:[1,0]
	v_div_fixup_f32 v170, v136, v170, 1.0
	v_mul_f32_e32 v136, 0xbfb8aa3b, v182
	v_exp_f32_e32 v184, v136
	v_mul_f32_e32 v136, 0xbfb8aa3b, v183
	v_exp_f32_e32 v185, v136
	v_pk_mul_f32 v[168:169], v[170:171], v[168:169]
	v_lshlrev_b32_e32 v170, 16, v138
	v_and_b32_e32 v171, 0xffff0000, v138
	v_pk_mul_f32 v[170:171], v[142:143], v[170:171] op_sel_hi:[0,1]
	v_pk_mul_f32 v[170:171], v[128:129], v[170:171]
	s_nop 0
	v_pk_mul_f32 v[170:171], v[182:183], v[170:171]
	v_pk_add_f32 v[182:183], v[184:185], 1.0 op_sel_hi:[1,0]
	s_nop 0
	v_div_scale_f32 v136, s[26:27], v183, v183, 1.0
	v_rcp_f32_e32 v138, v136
	s_nop 0
	v_fma_f32 v143, -v136, v138, 1.0
	v_fmac_f32_e32 v138, v143, v138
	v_div_scale_f32 v143, vcc, 1.0, v183, 1.0
	v_mul_f32_e32 v165, v143, v138
	v_fma_f32 v167, -v136, v165, v143
	v_fmac_f32_e32 v165, v167, v138
	v_fma_f32 v136, -v136, v165, v143
	v_div_fmas_f32 v136, v136, v138, v165
	v_div_fixup_f32 v183, v136, v183, 1.0
	v_div_scale_f32 v136, s[26:27], v182, v182, 1.0
	v_rcp_f32_e32 v138, v136
	s_nop 0
	v_fma_f32 v143, -v136, v138, 1.0
	v_fmac_f32_e32 v138, v143, v138
	v_div_scale_f32 v143, vcc, 1.0, v182, 1.0
	v_mul_f32_e32 v165, v143, v138
	v_fma_f32 v167, -v136, v165, v143
	v_fmac_f32_e32 v165, v167, v138
	v_fma_f32 v136, -v136, v165, v143
	v_div_fmas_f32 v136, v136, v138, v165
	v_div_fixup_f32 v182, v136, v182, 1.0
	v_pk_mul_f32 v[170:171], v[182:183], v[170:171]
	v_pk_mul_f32 v[182:183], v[38:39], v[148:149] op_sel_hi:[1,0]
	v_lshlrev_b32_e32 v136, 16, v137
	v_mul_f32_e32 v138, 0xbfb8aa3b, v182
	v_exp_f32_e32 v184, v138
	v_mul_f32_e32 v138, 0xbfb8aa3b, v183
	v_exp_f32_e32 v185, v138
	v_and_b32_e32 v137, 0xffff0000, v137
	v_pk_mul_f32 v[136:137], v[142:143], v[136:137] op_sel_hi:[0,1]
	v_pk_mul_f32 v[136:137], v[134:135], v[136:137]
	s_nop 0
	v_pk_mul_f32 v[136:137], v[182:183], v[136:137]
	v_pk_add_f32 v[182:183], v[184:185], 1.0 op_sel_hi:[1,0]
	s_nop 0
	v_div_scale_f32 v138, s[26:27], v183, v183, 1.0
	v_rcp_f32_e32 v143, v138
	s_nop 0
	v_fma_f32 v165, -v138, v143, 1.0
	v_fmac_f32_e32 v143, v165, v143
	v_div_scale_f32 v165, vcc, 1.0, v183, 1.0
	v_mul_f32_e32 v167, v165, v143
	v_fma_f32 v184, -v138, v167, v165
	v_fmac_f32_e32 v167, v184, v143
	v_fma_f32 v138, -v138, v167, v165
	v_div_fmas_f32 v138, v138, v143, v167
	v_div_fixup_f32 v183, v138, v183, 1.0
	v_div_scale_f32 v138, s[26:27], v182, v182, 1.0
	v_rcp_f32_e32 v143, v138
	s_nop 0
	v_fma_f32 v165, -v138, v143, 1.0
	v_fmac_f32_e32 v143, v165, v143
	v_div_scale_f32 v165, vcc, 1.0, v182, 1.0
	v_mul_f32_e32 v167, v165, v143
	v_fma_f32 v184, -v138, v167, v165
	v_fmac_f32_e32 v167, v184, v143
	v_fma_f32 v138, -v138, v167, v165
	v_div_fmas_f32 v138, v138, v143, v167
	v_div_fixup_f32 v182, v138, v182, 1.0
	v_pk_mul_f32 v[182:183], v[182:183], v[136:137]
	v_lshlrev_b32_e32 v136, 16, v139
	v_and_b32_e32 v137, 0xffff0000, v139
	v_pk_mul_f32 v[138:139], v[34:35], v[148:149] op_sel_hi:[1,0]
	s_nop 0
	v_mul_f32_e32 v143, 0xbfb8aa3b, v138
	v_pk_mul_f32 v[136:137], v[142:143], v[136:137] op_sel_hi:[0,1]
	v_pk_mul_f32 v[136:137], v[130:131], v[136:137]
	v_exp_f32_e32 v184, v143
	v_pk_mul_f32 v[136:137], v[138:139], v[136:137]
	v_mul_f32_e32 v138, 0xbfb8aa3b, v139
	v_exp_f32_e32 v185, v138
	s_nop 0
	v_pk_add_f32 v[138:139], v[184:185], 1.0 op_sel_hi:[1,0]
	s_nop 0
	v_div_scale_f32 v142, s[26:27], v139, v139, 1.0
	v_rcp_f32_e32 v143, v142
	s_nop 0
	v_fma_f32 v148, -v142, v143, 1.0
	v_fmac_f32_e32 v143, v148, v143
	v_div_scale_f32 v148, vcc, 1.0, v139, 1.0
	v_mul_f32_e32 v165, v148, v143
	v_fma_f32 v167, -v142, v165, v148
	v_fmac_f32_e32 v165, v167, v143
	v_fma_f32 v142, -v142, v165, v148
	v_div_fmas_f32 v142, v142, v143, v165
	v_div_fixup_f32 v139, v142, v139, 1.0
	v_div_scale_f32 v142, s[26:27], v138, v138, 1.0
	v_rcp_f32_e32 v143, v142
	s_mov_b32 s26, 0x3b800000
	s_mov_b32 s27, 0x3b800000
	v_fma_f32 v148, -v142, v143, 1.0
	v_fmac_f32_e32 v143, v148, v143
	v_div_scale_f32 v148, vcc, 1.0, v138, 1.0
	v_mul_f32_e32 v165, v148, v143
	v_fma_f32 v167, -v142, v165, v148
	v_fmac_f32_e32 v165, v167, v143
	v_fma_f32 v142, -v142, v165, v148
	v_div_fmas_f32 v142, v142, v143, v165
	v_div_fixup_f32 v138, v142, v138, 1.0
	v_pk_mul_f32 v[142:143], v[138:139], v[136:137]
	v_cvt_pk_bf16_f32 v136, v168, v169
	v_cvt_pk_bf16_f32 v137, v182, v183
	v_cvt_pk_bf16_f32 v138, v170, v171
	v_cvt_pk_bf16_f32 v139, v142, v143
	global_store_dwordx4 v[172:173], v[136:139], off offset:256
	s_and_b64 vcc, exec, s[44:45]
	s_nop 0
	v_lshl_add_u64 v[138:139], v[198:199], 2, v[190:191]
	global_load_dwordx4 v[168:171], v[138:139], off
	global_load_dwordx4 v[232:235], v[138:139], off offset:16
	s_waitcnt vmcnt(0)
	v_mov_b32_e32 v136, v169
	v_mov_b32_e32 v137, v170
	v_mov_b32_e32 v169, v171
	v_pk_add_f32 v[136:137], v[136:137], v[168:169]
	s_nop 0
	v_pk_add_f32 v[136:137], v[136:137], v[136:137] op_sel:[0,1] op_sel_hi:[1,0]
	s_cbranch_vccnz .LBB0_248
	v_mov_b64_e32 v[168:169], v[232:233]
	v_mov_b64_e32 v[170:171], v[234:235]
	s_mov_b32 s27, 0x3b000000
	v_mov_b32_e32 v138, v169
	v_mov_b32_e32 v139, v170
	v_mov_b32_e32 v169, v171
	v_pk_add_f32 v[138:139], v[138:139], v[168:169]
	s_nop 0
	v_add_f32_e32 v137, v138, v139
	v_add_f32_e32 v136, v136, v137
; DI unsigned pk(float lo, float hi) { f32x2 v = {lo, hi}; bf2_t b = __builtin_convertvector(v, bf2_t); return __builtin_bit_cast(unsigned, b); }
; DI float bflo(unsigned w) { return __uint_as_float(w << 16); }
; DI float bfhi(unsigned w) { return __uint_as_float(w & 0xffff0000u); }
; DI float sigmoidf_(float x) { return 1.0f / (1.0f + __expf(-x)); }
; DI void gemm_epilogue(const GemmDesc& g, f32x4 (&acc)[2][2][4][2], int brow, int bcol, int wr, int wc, int fr, int fq) {
;     ...
;           const int row = rowb + ai * HALF + m * 16;
;           float rs;
;           { const float* sp = g.f0 + (size_t)row * 32 + head * 8;
;             const f32x4 s0 = gld<f32x4>(sp); float ssum = (s0[0] + s0[1]) + (s0[2] + s0[3]);
;             if (g.dvshift == 9) { const f32x4 s1 = gld<f32x4>(sp + 4); ssum += (s1[0] + s1[1]) + (s1[2] + s1[3]); }
;             rs = rsqrtf(ssum * (g.dvshift == 9 ? (1.0f / 512.0f) : (1.0f / 256.0f)) + EPS); }
;           bf16_t* op = g.o0 + (size_t)row * N + col;
;           const u32x4 ow = gld<u32x4>(op);
;           const float ru = gld<float>(g.rowscale + row);
;           const f32x4 v0 = acc[ai][bj][m][0] * ru, v1 = acc[ai][bj][m][1] * ru;
;           float o[8] = {bflo(ow.x), bfhi(ow.x), bflo(ow.y), bfhi(ow.y), bflo(ow.z), bfhi(ow.z), bflo(ow.w), bfhi(ow.w)};
; #pragma unroll
;           for (int j = 0; j < 4; ++j) { o[j] = o[j] * rs * g0[j] * v0[j] * sigmoidf_(v0[j]); o[4 + j] = o[4 + j] * rs * g1[j] * v1[j] * sigmoidf_(v1[j]); }
;           u32x4 w; w.x = pk(o[0], o[1]); w.y = pk(o[2], o[3]); w.z = pk(o[4], o[5]); w.w = pk(o[6], o[7]);
;           gst<u32x4>(op, w);
.LBB0_248:
	v_fma_f32 v136, s27, v136, v204
	v_cmp_gt_f32_e32 vcc, s33, v136
	v_mul_f32_e32 v137, 0x4b800000, v136
	s_nop 0
	v_cndmask_b32_e32 v136, v136, v137, vcc
	v_rsq_f32_e32 v136, v136
	s_nop 0
	v_mul_f32_e32 v137, 0x45800000, v136
	v_cndmask_b32_e32 v142, v136, v137, vcc
	global_load_dwordx4 v[136:139], v[174:175], off offset:256
	global_load_dword v148, v[140:141], off offset:512
	s_waitcnt vmcnt(1)
	v_lshlrev_b32_e32 v168, 16, v136
	s_waitcnt vmcnt(0)
	v_pk_mul_f32 v[170:171], v[28:29], v[148:149] op_sel_hi:[1,0]
	v_and_b32_e32 v169, 0xffff0000, v136
	v_mul_f32_e32 v136, 0xbfb8aa3b, v170
	v_exp_f32_e32 v172, v136
	v_mul_f32_e32 v136, 0xbfb8aa3b, v171
	v_exp_f32_e32 v173, v136
	v_pk_mul_f32 v[168:169], v[142:143], v[168:169] op_sel_hi:[0,1]
	v_pk_mul_f32 v[168:169], v[132:133], v[168:169]
	s_nop 0
	v_pk_mul_f32 v[168:169], v[170:171], v[168:169]
	v_pk_add_f32 v[170:171], v[172:173], 1.0 op_sel_hi:[1,0]
	s_nop 0
	v_div_scale_f32 v136, s[46:47], v171, v171, 1.0
	v_rcp_f32_e32 v143, v136
	s_nop 0
	v_fma_f32 v165, -v136, v143, 1.0
	v_fmac_f32_e32 v143, v165, v143
	v_div_scale_f32 v165, vcc, 1.0, v171, 1.0
	v_mul_f32_e32 v167, v165, v143
	v_fma_f32 v172, -v136, v167, v165
	v_fmac_f32_e32 v167, v172, v143
	v_fma_f32 v136, -v136, v167, v165
	v_div_fmas_f32 v136, v136, v143, v167
	v_div_fixup_f32 v171, v136, v171, 1.0
	v_div_scale_f32 v136, s[46:47], v170, v170, 1.0
	v_rcp_f32_e32 v143, v136
	s_nop 0
	v_fma_f32 v165, -v136, v143, 1.0
	v_fmac_f32_e32 v143, v165, v143
	v_div_scale_f32 v165, vcc, 1.0, v170, 1.0
	v_mul_f32_e32 v167, v165, v143
	v_fma_f32 v172, -v136, v167, v165
	v_fmac_f32_e32 v167, v172, v143
	v_fma_f32 v136, -v136, v167, v165
	v_div_fmas_f32 v136, v136, v143, v167
	v_pk_mul_f32 v[172:173], v[24:25], v[148:149] op_sel_hi:[1,0]
	v_div_fixup_f32 v170, v136, v170, 1.0
	v_mul_f32_e32 v136, 0xbfb8aa3b, v172
	v_exp_f32_e32 v182, v136
	v_mul_f32_e32 v136, 0xbfb8aa3b, v173
	v_exp_f32_e32 v183, v136
	v_pk_mul_f32 v[168:169], v[170:171], v[168:169]
	v_lshlrev_b32_e32 v170, 16, v138
	v_and_b32_e32 v171, 0xffff0000, v138
	v_pk_mul_f32 v[170:171], v[142:143], v[170:171] op_sel_hi:[0,1]
	v_pk_mul_f32 v[170:171], v[128:129], v[170:171]
	s_nop 0
	v_pk_mul_f32 v[170:171], v[172:173], v[170:171]
	v_pk_add_f32 v[172:173], v[182:183], 1.0 op_sel_hi:[1,0]
	s_nop 0
	v_div_scale_f32 v136, s[46:47], v173, v173, 1.0
	v_rcp_f32_e32 v138, v136
	s_nop 0
	v_fma_f32 v143, -v136, v138, 1.0
	v_fmac_f32_e32 v138, v143, v138
	v_div_scale_f32 v143, vcc, 1.0, v173, 1.0
	v_mul_f32_e32 v165, v143, v138
	v_fma_f32 v167, -v136, v165, v143
	v_fmac_f32_e32 v165, v167, v138
	v_fma_f32 v136, -v136, v165, v143
	v_div_fmas_f32 v136, v136, v138, v165
	v_div_fixup_f32 v173, v136, v173, 1.0
	v_div_scale_f32 v136, s[46:47], v172, v172, 1.0
	v_rcp_f32_e32 v138, v136
	s_nop 0
	v_fma_f32 v143, -v136, v138, 1.0
	v_fmac_f32_e32 v138, v143, v138
	v_div_scale_f32 v143, vcc, 1.0, v172, 1.0
	v_mul_f32_e32 v165, v143, v138
	v_fma_f32 v167, -v136, v165, v143
	v_fmac_f32_e32 v165, v167, v138
	v_fma_f32 v136, -v136, v165, v143
	v_div_fmas_f32 v136, v136, v138, v165
	v_div_fixup_f32 v172, v136, v172, 1.0
	v_pk_mul_f32 v[170:171], v[172:173], v[170:171]
	v_pk_mul_f32 v[172:173], v[30:31], v[148:149] op_sel_hi:[1,0]
	v_lshlrev_b32_e32 v136, 16, v137
	v_mul_f32_e32 v138, 0xbfb8aa3b, v172
	v_exp_f32_e32 v182, v138
	v_mul_f32_e32 v138, 0xbfb8aa3b, v173
	v_exp_f32_e32 v183, v138
	v_and_b32_e32 v137, 0xffff0000, v137
	v_pk_mul_f32 v[136:137], v[142:143], v[136:137] op_sel_hi:[0,1]
	v_pk_mul_f32 v[136:137], v[134:135], v[136:137]
	s_nop 0
	v_pk_mul_f32 v[136:137], v[172:173], v[136:137]
	v_pk_add_f32 v[172:173], v[182:183], 1.0 op_sel_hi:[1,0]
	s_nop 0
	v_div_scale_f32 v138, s[46:47], v173, v173, 1.0
	v_rcp_f32_e32 v143, v138
	s_nop 0
	v_fma_f32 v165, -v138, v143, 1.0
	v_fmac_f32_e32 v143, v165, v143
	v_div_scale_f32 v165, vcc, 1.0, v173, 1.0
	v_mul_f32_e32 v167, v165, v143
	v_fma_f32 v182, -v138, v167, v165
	v_fmac_f32_e32 v167, v182, v143
	v_fma_f32 v138, -v138, v167, v165
	v_div_fmas_f32 v138, v138, v143, v167
	v_div_fixup_f32 v173, v138, v173, 1.0
	v_div_scale_f32 v138, s[46:47], v172, v172, 1.0
	v_rcp_f32_e32 v143, v138
	s_nop 0
	v_fma_f32 v165, -v138, v143, 1.0
	v_fmac_f32_e32 v143, v165, v143
	v_div_scale_f32 v165, vcc, 1.0, v172, 1.0
	v_mul_f32_e32 v167, v165, v143
	v_fma_f32 v182, -v138, v167, v165
	v_fmac_f32_e32 v167, v182, v143
	v_fma_f32 v138, -v138, v167, v165
	v_div_fmas_f32 v138, v138, v143, v167
	v_div_fixup_f32 v172, v138, v172, 1.0
	v_pk_mul_f32 v[172:173], v[172:173], v[136:137]
	v_lshlrev_b32_e32 v136, 16, v139
	v_and_b32_e32 v137, 0xffff0000, v139
	v_pk_mul_f32 v[138:139], v[26:27], v[148:149] op_sel_hi:[1,0]
	s_nop 0
	v_mul_f32_e32 v143, 0xbfb8aa3b, v138
	v_pk_mul_f32 v[136:137], v[142:143], v[136:137] op_sel_hi:[0,1]
	v_pk_mul_f32 v[136:137], v[130:131], v[136:137]
	v_exp_f32_e32 v182, v143
	v_pk_mul_f32 v[136:137], v[138:139], v[136:137]
	v_mul_f32_e32 v138, 0xbfb8aa3b, v139
	v_exp_f32_e32 v183, v138
	s_nop 0
	v_pk_add_f32 v[138:139], v[182:183], 1.0 op_sel_hi:[1,0]
	s_nop 0
	v_div_scale_f32 v142, s[46:47], v139, v139, 1.0
	v_rcp_f32_e32 v143, v142
	s_nop 0
	v_fma_f32 v148, -v142, v143, 1.0
	v_fmac_f32_e32 v143, v148, v143
	v_div_scale_f32 v148, vcc, 1.0, v139, 1.0
	v_mul_f32_e32 v165, v148, v143
	v_fma_f32 v167, -v142, v165, v148
	v_fmac_f32_e32 v165, v167, v143
	v_fma_f32 v142, -v142, v165, v148
	v_div_fmas_f32 v142, v142, v143, v165
	v_div_fixup_f32 v139, v142, v139, 1.0
	v_div_scale_f32 v142, s[46:47], v138, v138, 1.0
	v_rcp_f32_e32 v143, v142
	s_nop 0
	v_fma_f32 v148, -v142, v143, 1.0
	v_fmac_f32_e32 v143, v148, v143
	v_div_scale_f32 v148, vcc, 1.0, v138, 1.0
	v_mul_f32_e32 v165, v148, v143
	v_fma_f32 v167, -v142, v165, v148
	v_fmac_f32_e32 v165, v167, v143
	v_fma_f32 v142, -v142, v165, v148
	v_div_fmas_f32 v142, v142, v143, v165
	v_div_fixup_f32 v138, v142, v138, 1.0
	v_pk_mul_f32 v[142:143], v[138:139], v[136:137]
	v_cvt_pk_bf16_f32 v136, v168, v169
	v_cvt_pk_bf16_f32 v137, v172, v173
	v_cvt_pk_bf16_f32 v138, v170, v171
	v_cvt_pk_bf16_f32 v139, v142, v143
	global_store_dwordx4 v[174:175], v[136:139], off offset:256
	s_and_b64 vcc, exec, s[44:45]
	s_nop 0
	v_lshl_add_u64 v[138:139], v[198:199], 2, v[192:193]
	global_load_dwordx4 v[168:171], v[138:139], off
	global_load_dwordx4 v[232:235], v[138:139], off offset:16
	s_waitcnt vmcnt(0)
	v_mov_b32_e32 v136, v169
	v_mov_b32_e32 v137, v170
	v_mov_b32_e32 v169, v171
	v_pk_add_f32 v[136:137], v[136:137], v[168:169]
	s_nop 0
	v_pk_add_f32 v[136:137], v[136:137], v[136:137] op_sel:[0,1] op_sel_hi:[1,0]
	s_cbranch_vccnz .LBB0_250
	v_mov_b64_e32 v[168:169], v[232:233]
	v_mov_b64_e32 v[170:171], v[234:235]
	s_mov_b32 s26, 0x3b000000
	v_mov_b32_e32 v138, v169
	v_mov_b32_e32 v139, v170
	v_mov_b32_e32 v169, v171
	v_pk_add_f32 v[138:139], v[138:139], v[168:169]
	s_nop 0
	v_add_f32_e32 v137, v138, v139
	v_add_f32_e32 v136, v136, v137
; DI unsigned pk(float lo, float hi) { f32x2 v = {lo, hi}; bf2_t b = __builtin_convertvector(v, bf2_t); return __builtin_bit_cast(unsigned, b); }
; DI float bflo(unsigned w) { return __uint_as_float(w << 16); }
; DI float bfhi(unsigned w) { return __uint_as_float(w & 0xffff0000u); }
; DI float sigmoidf_(float x) { return 1.0f / (1.0f + __expf(-x)); }
; DI void gemm_epilogue(const GemmDesc& g, f32x4 (&acc)[2][2][4][2], int brow, int bcol, int wr, int wc, int fr, int fq) {
;     ...
;           const int row = rowb + ai * HALF + m * 16;
;           float rs;
;           { const float* sp = g.f0 + (size_t)row * 32 + head * 8;
;             const f32x4 s0 = gld<f32x4>(sp); float ssum = (s0[0] + s0[1]) + (s0[2] + s0[3]);
;             if (g.dvshift == 9) { const f32x4 s1 = gld<f32x4>(sp + 4); ssum += (s1[0] + s1[1]) + (s1[2] + s1[3]); }
;             rs = rsqrtf(ssum * (g.dvshift == 9 ? (1.0f / 512.0f) : (1.0f / 256.0f)) + EPS); }
;           bf16_t* op = g.o0 + (size_t)row * N + col;
;           const u32x4 ow = gld<u32x4>(op);
;           const float ru = gld<float>(g.rowscale + row);
;           const f32x4 v0 = acc[ai][bj][m][0] * ru, v1 = acc[ai][bj][m][1] * ru;
;           float o[8] = {bflo(ow.x), bfhi(ow.x), bflo(ow.y), bfhi(ow.y), bflo(ow.z), bfhi(ow.z), bflo(ow.w), bfhi(ow.w)};
; #pragma unroll
;           for (int j = 0; j < 4; ++j) { o[j] = o[j] * rs * g0[j] * v0[j] * sigmoidf_(v0[j]); o[4 + j] = o[4 + j] * rs * g1[j] * v1[j] * sigmoidf_(v1[j]); }
;           u32x4 w; w.x = pk(o[0], o[1]); w.y = pk(o[2], o[3]); w.z = pk(o[4], o[5]); w.w = pk(o[6], o[7]);
;           gst<u32x4>(op, w);
.LBB0_250:
	v_fma_f32 v136, s26, v136, v204
	v_cmp_gt_f32_e32 vcc, s33, v136
	v_mul_f32_e32 v137, 0x4b800000, v136
	s_nop 0
	v_cndmask_b32_e32 v136, v136, v137, vcc
	v_rsq_f32_e32 v136, v136
	s_nop 0
	v_mul_f32_e32 v137, 0x45800000, v136
	v_cndmask_b32_e32 v142, v136, v137, vcc
	global_load_dwordx4 v[136:139], v[176:177], off offset:256
	global_load_dword v148, v[140:141], off offset:576
	s_waitcnt vmcnt(1)
	v_lshlrev_b32_e32 v168, 16, v136
	s_waitcnt vmcnt(0)
	v_pk_mul_f32 v[170:171], v[20:21], v[148:149] op_sel_hi:[1,0]
	v_and_b32_e32 v169, 0xffff0000, v136
	v_mul_f32_e32 v136, 0xbfb8aa3b, v170
	v_exp_f32_e32 v172, v136
	v_mul_f32_e32 v136, 0xbfb8aa3b, v171
	v_exp_f32_e32 v173, v136
	v_pk_mul_f32 v[168:169], v[142:143], v[168:169] op_sel_hi:[0,1]
	v_pk_mul_f32 v[168:169], v[132:133], v[168:169]
	s_nop 0
	v_pk_mul_f32 v[168:169], v[170:171], v[168:169]
	v_pk_add_f32 v[170:171], v[172:173], 1.0 op_sel_hi:[1,0]
	s_nop 0
	v_div_scale_f32 v136, s[26:27], v171, v171, 1.0
	v_rcp_f32_e32 v143, v136
	s_nop 0
	v_fma_f32 v165, -v136, v143, 1.0
	v_fmac_f32_e32 v143, v165, v143
	v_div_scale_f32 v165, vcc, 1.0, v171, 1.0
	v_mul_f32_e32 v167, v165, v143
	v_fma_f32 v172, -v136, v167, v165
	v_fmac_f32_e32 v167, v172, v143
	v_fma_f32 v136, -v136, v167, v165
	v_div_fmas_f32 v136, v136, v143, v167
	v_div_fixup_f32 v171, v136, v171, 1.0
	v_div_scale_f32 v136, s[26:27], v170, v170, 1.0
	v_rcp_f32_e32 v143, v136
	s_nop 0
	v_fma_f32 v165, -v136, v143, 1.0
	v_fmac_f32_e32 v143, v165, v143
	v_div_scale_f32 v165, vcc, 1.0, v170, 1.0
	v_mul_f32_e32 v167, v165, v143
	v_fma_f32 v172, -v136, v167, v165
	v_fmac_f32_e32 v167, v172, v143
	v_fma_f32 v136, -v136, v167, v165
	v_div_fmas_f32 v136, v136, v143, v167
	v_pk_mul_f32 v[172:173], v[16:17], v[148:149] op_sel_hi:[1,0]
	v_div_fixup_f32 v170, v136, v170, 1.0
	v_mul_f32_e32 v136, 0xbfb8aa3b, v172
	v_exp_f32_e32 v174, v136
	v_mul_f32_e32 v136, 0xbfb8aa3b, v173
	v_exp_f32_e32 v175, v136
	v_pk_mul_f32 v[168:169], v[170:171], v[168:169]
	v_lshlrev_b32_e32 v170, 16, v138
	v_and_b32_e32 v171, 0xffff0000, v138
	v_pk_mul_f32 v[170:171], v[142:143], v[170:171] op_sel_hi:[0,1]
	v_pk_mul_f32 v[170:171], v[128:129], v[170:171]
	s_nop 0
	v_pk_mul_f32 v[170:171], v[172:173], v[170:171]
	v_pk_add_f32 v[172:173], v[174:175], 1.0 op_sel_hi:[1,0]
	s_nop 0
	v_div_scale_f32 v136, s[26:27], v173, v173, 1.0
	v_rcp_f32_e32 v138, v136
	s_nop 0
	v_fma_f32 v143, -v136, v138, 1.0
	v_fmac_f32_e32 v138, v143, v138
	v_div_scale_f32 v143, vcc, 1.0, v173, 1.0
	v_mul_f32_e32 v165, v143, v138
	v_fma_f32 v167, -v136, v165, v143
	v_fmac_f32_e32 v165, v167, v138
	v_fma_f32 v136, -v136, v165, v143
	v_div_fmas_f32 v136, v136, v138, v165
	v_div_fixup_f32 v173, v136, v173, 1.0
	v_div_scale_f32 v136, s[26:27], v172, v172, 1.0
	v_rcp_f32_e32 v138, v136
	s_nop 0
	v_fma_f32 v143, -v136, v138, 1.0
	v_fmac_f32_e32 v138, v143, v138
	v_div_scale_f32 v143, vcc, 1.0, v172, 1.0
	v_mul_f32_e32 v165, v143, v138
	v_fma_f32 v167, -v136, v165, v143
	v_fmac_f32_e32 v165, v167, v138
	v_fma_f32 v136, -v136, v165, v143
	v_div_fmas_f32 v136, v136, v138, v165
	v_div_fixup_f32 v172, v136, v172, 1.0
	v_pk_mul_f32 v[170:171], v[172:173], v[170:171]
	v_pk_mul_f32 v[172:173], v[22:23], v[148:149] op_sel_hi:[1,0]
	v_lshlrev_b32_e32 v136, 16, v137
	v_mul_f32_e32 v138, 0xbfb8aa3b, v172
	v_exp_f32_e32 v174, v138
	v_mul_f32_e32 v138, 0xbfb8aa3b, v173
	v_exp_f32_e32 v175, v138
	v_and_b32_e32 v137, 0xffff0000, v137
	v_pk_mul_f32 v[136:137], v[142:143], v[136:137] op_sel_hi:[0,1]
	v_pk_mul_f32 v[136:137], v[134:135], v[136:137]
	s_nop 0
	v_pk_mul_f32 v[136:137], v[172:173], v[136:137]
	v_pk_add_f32 v[172:173], v[174:175], 1.0 op_sel_hi:[1,0]
	s_nop 0
	v_div_scale_f32 v138, s[26:27], v173, v173, 1.0
	v_rcp_f32_e32 v143, v138
	s_nop 0
	v_fma_f32 v165, -v138, v143, 1.0
	v_fmac_f32_e32 v143, v165, v143
	v_div_scale_f32 v165, vcc, 1.0, v173, 1.0
	v_mul_f32_e32 v167, v165, v143
	v_fma_f32 v174, -v138, v167, v165
	v_fmac_f32_e32 v167, v174, v143
	v_fma_f32 v138, -v138, v167, v165
	v_div_fmas_f32 v138, v138, v143, v167
	v_div_fixup_f32 v173, v138, v173, 1.0
	v_div_scale_f32 v138, s[26:27], v172, v172, 1.0
	v_rcp_f32_e32 v143, v138
	s_nop 0
	v_fma_f32 v165, -v138, v143, 1.0
	v_fmac_f32_e32 v143, v165, v143
	v_div_scale_f32 v165, vcc, 1.0, v172, 1.0
	v_mul_f32_e32 v167, v165, v143
	v_fma_f32 v174, -v138, v167, v165
	v_fmac_f32_e32 v167, v174, v143
	v_fma_f32 v138, -v138, v167, v165
	v_div_fmas_f32 v138, v138, v143, v167
	v_div_fixup_f32 v172, v138, v172, 1.0
	v_pk_mul_f32 v[172:173], v[172:173], v[136:137]
	v_lshlrev_b32_e32 v136, 16, v139
	v_and_b32_e32 v137, 0xffff0000, v139
	v_pk_mul_f32 v[138:139], v[18:19], v[148:149] op_sel_hi:[1,0]
	s_nop 0
	v_mul_f32_e32 v143, 0xbfb8aa3b, v138
	v_pk_mul_f32 v[136:137], v[142:143], v[136:137] op_sel_hi:[0,1]
	v_pk_mul_f32 v[136:137], v[130:131], v[136:137]
	v_exp_f32_e32 v174, v143
	v_pk_mul_f32 v[136:137], v[138:139], v[136:137]
	v_mul_f32_e32 v138, 0xbfb8aa3b, v139
	v_exp_f32_e32 v175, v138
	s_nop 0
	v_pk_add_f32 v[138:139], v[174:175], 1.0 op_sel_hi:[1,0]
	s_nop 0
	v_div_scale_f32 v142, s[26:27], v139, v139, 1.0
	v_rcp_f32_e32 v143, v142
	s_nop 0
	v_fma_f32 v148, -v142, v143, 1.0
	v_fmac_f32_e32 v143, v148, v143
	v_div_scale_f32 v148, vcc, 1.0, v139, 1.0
	v_mul_f32_e32 v165, v148, v143
	v_fma_f32 v167, -v142, v165, v148
	v_fmac_f32_e32 v165, v167, v143
	v_fma_f32 v142, -v142, v165, v148
	v_div_fmas_f32 v142, v142, v143, v165
	v_div_fixup_f32 v139, v142, v139, 1.0
	v_div_scale_f32 v142, s[26:27], v138, v138, 1.0
	v_rcp_f32_e32 v143, v142
	s_mov_b32 s26, 0x3b800000
	s_mov_b32 s27, 0x3b800000
	v_fma_f32 v148, -v142, v143, 1.0
	v_fmac_f32_e32 v143, v148, v143
	v_div_scale_f32 v148, vcc, 1.0, v138, 1.0
	v_mul_f32_e32 v165, v148, v143
	v_fma_f32 v167, -v142, v165, v148
	v_fmac_f32_e32 v165, v167, v143
	v_fma_f32 v142, -v142, v165, v148
	v_div_fmas_f32 v142, v142, v143, v165
	v_div_fixup_f32 v138, v142, v138, 1.0
	v_pk_mul_f32 v[142:143], v[138:139], v[136:137]
	v_cvt_pk_bf16_f32 v136, v168, v169
	v_cvt_pk_bf16_f32 v137, v172, v173
	v_cvt_pk_bf16_f32 v138, v170, v171
	v_cvt_pk_bf16_f32 v139, v142, v143
	global_store_dwordx4 v[176:177], v[136:139], off offset:256
	s_and_b64 vcc, exec, s[44:45]
	s_nop 0
	v_lshl_add_u64 v[138:139], v[198:199], 2, v[194:195]
	global_load_dwordx4 v[168:171], v[138:139], off
	global_load_dwordx4 v[232:235], v[138:139], off offset:16
	s_waitcnt vmcnt(0)
	v_mov_b32_e32 v136, v169
	v_mov_b32_e32 v137, v170
	v_mov_b32_e32 v169, v171
	v_pk_add_f32 v[136:137], v[136:137], v[168:169]
	s_nop 0
	v_pk_add_f32 v[136:137], v[136:137], v[136:137] op_sel:[0,1] op_sel_hi:[1,0]
	s_cbranch_vccnz .LBB0_252
	v_mov_b64_e32 v[168:169], v[232:233]
	v_mov_b64_e32 v[170:171], v[234:235]
	s_mov_b32 s27, 0x3b000000
	v_mov_b32_e32 v138, v169
	v_mov_b32_e32 v139, v170
	v_mov_b32_e32 v169, v171
	v_pk_add_f32 v[138:139], v[138:139], v[168:169]
	s_nop 0
	v_add_f32_e32 v137, v138, v139
	v_add_f32_e32 v136, v136, v137
; DI unsigned pk(float lo, float hi) { f32x2 v = {lo, hi}; bf2_t b = __builtin_convertvector(v, bf2_t); return __builtin_bit_cast(unsigned, b); }
; DI float bflo(unsigned w) { return __uint_as_float(w << 16); }
; DI float bfhi(unsigned w) { return __uint_as_float(w & 0xffff0000u); }
; DI float sigmoidf_(float x) { return 1.0f / (1.0f + __expf(-x)); }
; DI void gemm_epilogue(const GemmDesc& g, f32x4 (&acc)[2][2][4][2], int brow, int bcol, int wr, int wc, int fr, int fq) {
;     ...
;           const int row = rowb + ai * HALF + m * 16;
;           float rs;
;           { const float* sp = g.f0 + (size_t)row * 32 + head * 8;
;             const f32x4 s0 = gld<f32x4>(sp); float ssum = (s0[0] + s0[1]) + (s0[2] + s0[3]);
;             if (g.dvshift == 9) { const f32x4 s1 = gld<f32x4>(sp + 4); ssum += (s1[0] + s1[1]) + (s1[2] + s1[3]); }
;             rs = rsqrtf(ssum * (g.dvshift == 9 ? (1.0f / 512.0f) : (1.0f / 256.0f)) + EPS); }
;           bf16_t* op = g.o0 + (size_t)row * N + col;
;           const u32x4 ow = gld<u32x4>(op);
;           const float ru = gld<float>(g.rowscale + row);
;           const f32x4 v0 = acc[ai][bj][m][0] * ru, v1 = acc[ai][bj][m][1] * ru;
;           float o[8] = {bflo(ow.x), bfhi(ow.x), bflo(ow.y), bfhi(ow.y), bflo(ow.z), bfhi(ow.z), bflo(ow.w), bfhi(ow.w)};
; #pragma unroll
;           for (int j = 0; j < 4; ++j) { o[j] = o[j] * rs * g0[j] * v0[j] * sigmoidf_(v0[j]); o[4 + j] = o[4 + j] * rs * g1[j] * v1[j] * sigmoidf_(v1[j]); }
;           u32x4 w; w.x = pk(o[0], o[1]); w.y = pk(o[2], o[3]); w.z = pk(o[4], o[5]); w.w = pk(o[6], o[7]);
;           gst<u32x4>(op, w);
.LBB0_252:
	v_fma_f32 v136, s27, v136, v204
	v_cmp_gt_f32_e32 vcc, s33, v136
	v_mul_f32_e32 v137, 0x4b800000, v136
	s_nop 0
	v_cndmask_b32_e32 v136, v136, v137, vcc
	v_rsq_f32_e32 v136, v136
	s_nop 0
	v_mul_f32_e32 v137, 0x45800000, v136
	v_cndmask_b32_e32 v142, v136, v137, vcc
	global_load_dwordx4 v[136:139], v[178:179], off offset:256
	global_load_dword v148, v[140:141], off offset:640
	s_waitcnt vmcnt(1)
	v_lshlrev_b32_e32 v168, 16, v136
	s_waitcnt vmcnt(0)
	v_pk_mul_f32 v[170:171], v[12:13], v[148:149] op_sel_hi:[1,0]
	v_and_b32_e32 v169, 0xffff0000, v136
	v_mul_f32_e32 v136, 0xbfb8aa3b, v170
	v_exp_f32_e32 v172, v136
	v_mul_f32_e32 v136, 0xbfb8aa3b, v171
	v_exp_f32_e32 v173, v136
	v_pk_mul_f32 v[168:169], v[142:143], v[168:169] op_sel_hi:[0,1]
	v_pk_mul_f32 v[168:169], v[132:133], v[168:169]
	s_nop 0
	v_pk_mul_f32 v[168:169], v[170:171], v[168:169]
	v_pk_add_f32 v[170:171], v[172:173], 1.0 op_sel_hi:[1,0]
	s_nop 0
	v_div_scale_f32 v136, s[46:47], v171, v171, 1.0
	v_rcp_f32_e32 v143, v136
	s_nop 0
	v_fma_f32 v165, -v136, v143, 1.0
	v_fmac_f32_e32 v143, v165, v143
	v_div_scale_f32 v165, vcc, 1.0, v171, 1.0
	v_mul_f32_e32 v167, v165, v143
	v_fma_f32 v172, -v136, v167, v165
	v_fmac_f32_e32 v167, v172, v143
	v_fma_f32 v136, -v136, v167, v165
	v_div_fmas_f32 v136, v136, v143, v167
	v_div_fixup_f32 v171, v136, v171, 1.0
	v_div_scale_f32 v136, s[46:47], v170, v170, 1.0
	v_rcp_f32_e32 v143, v136
	s_nop 0
	v_fma_f32 v165, -v136, v143, 1.0
	v_fmac_f32_e32 v143, v165, v143
	v_div_scale_f32 v165, vcc, 1.0, v170, 1.0
	v_mul_f32_e32 v167, v165, v143
	v_fma_f32 v172, -v136, v167, v165
	v_fmac_f32_e32 v167, v172, v143
	v_fma_f32 v136, -v136, v167, v165
	v_div_fmas_f32 v136, v136, v143, v167
	v_pk_mul_f32 v[172:173], v[8:9], v[148:149] op_sel_hi:[1,0]
	v_div_fixup_f32 v170, v136, v170, 1.0
	v_mul_f32_e32 v136, 0xbfb8aa3b, v172
	v_exp_f32_e32 v174, v136
	v_mul_f32_e32 v136, 0xbfb8aa3b, v173
	v_exp_f32_e32 v175, v136
	v_pk_mul_f32 v[168:169], v[170:171], v[168:169]
	v_lshlrev_b32_e32 v170, 16, v138
	v_and_b32_e32 v171, 0xffff0000, v138
	v_pk_mul_f32 v[170:171], v[142:143], v[170:171] op_sel_hi:[0,1]
	v_pk_mul_f32 v[170:171], v[128:129], v[170:171]
	s_nop 0
	v_pk_mul_f32 v[170:171], v[172:173], v[170:171]
	v_pk_add_f32 v[172:173], v[174:175], 1.0 op_sel_hi:[1,0]
	s_nop 0
	v_div_scale_f32 v136, s[46:47], v173, v173, 1.0
	v_rcp_f32_e32 v138, v136
	s_nop 0
	v_fma_f32 v143, -v136, v138, 1.0
	v_fmac_f32_e32 v138, v143, v138
	v_div_scale_f32 v143, vcc, 1.0, v173, 1.0
	v_mul_f32_e32 v165, v143, v138
	v_fma_f32 v167, -v136, v165, v143
	v_fmac_f32_e32 v165, v167, v138
	v_fma_f32 v136, -v136, v165, v143
	v_div_fmas_f32 v136, v136, v138, v165
	v_div_fixup_f32 v173, v136, v173, 1.0
	v_div_scale_f32 v136, s[46:47], v172, v172, 1.0
	v_rcp_f32_e32 v138, v136
	s_nop 0
	v_fma_f32 v143, -v136, v138, 1.0
	v_fmac_f32_e32 v138, v143, v138
	v_div_scale_f32 v143, vcc, 1.0, v172, 1.0
	v_mul_f32_e32 v165, v143, v138
	v_fma_f32 v167, -v136, v165, v143
	v_fmac_f32_e32 v165, v167, v138
	v_fma_f32 v136, -v136, v165, v143
	v_div_fmas_f32 v136, v136, v138, v165
	v_div_fixup_f32 v172, v136, v172, 1.0
	v_pk_mul_f32 v[170:171], v[172:173], v[170:171]
	v_pk_mul_f32 v[172:173], v[14:15], v[148:149] op_sel_hi:[1,0]
	v_lshlrev_b32_e32 v136, 16, v137
	v_mul_f32_e32 v138, 0xbfb8aa3b, v172
	v_exp_f32_e32 v174, v138
	v_mul_f32_e32 v138, 0xbfb8aa3b, v173
	v_exp_f32_e32 v175, v138
	v_and_b32_e32 v137, 0xffff0000, v137
	v_pk_mul_f32 v[136:137], v[142:143], v[136:137] op_sel_hi:[0,1]
	v_pk_mul_f32 v[136:137], v[134:135], v[136:137]
	s_nop 0
	v_pk_mul_f32 v[136:137], v[172:173], v[136:137]
	v_pk_add_f32 v[172:173], v[174:175], 1.0 op_sel_hi:[1,0]
	s_nop 0
	v_div_scale_f32 v138, s[46:47], v173, v173, 1.0
	v_rcp_f32_e32 v143, v138
	s_nop 0
	v_fma_f32 v165, -v138, v143, 1.0
	v_fmac_f32_e32 v143, v165, v143
	v_div_scale_f32 v165, vcc, 1.0, v173, 1.0
	v_mul_f32_e32 v167, v165, v143
	v_fma_f32 v174, -v138, v167, v165
	v_fmac_f32_e32 v167, v174, v143
	v_fma_f32 v138, -v138, v167, v165
	v_div_fmas_f32 v138, v138, v143, v167
	v_div_fixup_f32 v173, v138, v173, 1.0
	v_div_scale_f32 v138, s[46:47], v172, v172, 1.0
	v_rcp_f32_e32 v143, v138
	s_nop 0
	v_fma_f32 v165, -v138, v143, 1.0
	v_fmac_f32_e32 v143, v165, v143
	v_div_scale_f32 v165, vcc, 1.0, v172, 1.0
	v_mul_f32_e32 v167, v165, v143
	v_fma_f32 v174, -v138, v167, v165
	v_fmac_f32_e32 v167, v174, v143
	v_fma_f32 v138, -v138, v167, v165
	v_div_fmas_f32 v138, v138, v143, v167
	v_div_fixup_f32 v172, v138, v172, 1.0
	v_pk_mul_f32 v[172:173], v[172:173], v[136:137]
	v_lshlrev_b32_e32 v136, 16, v139
	v_and_b32_e32 v137, 0xffff0000, v139
	v_pk_mul_f32 v[138:139], v[10:11], v[148:149] op_sel_hi:[1,0]
	s_nop 0
	v_mul_f32_e32 v143, 0xbfb8aa3b, v138
	v_pk_mul_f32 v[136:137], v[142:143], v[136:137] op_sel_hi:[0,1]
	v_pk_mul_f32 v[136:137], v[130:131], v[136:137]
	v_exp_f32_e32 v174, v143
	v_pk_mul_f32 v[136:137], v[138:139], v[136:137]
	v_mul_f32_e32 v138, 0xbfb8aa3b, v139
	v_exp_f32_e32 v175, v138
	s_nop 0
	v_pk_add_f32 v[138:139], v[174:175], 1.0 op_sel_hi:[1,0]
	s_nop 0
	v_div_scale_f32 v142, s[46:47], v139, v139, 1.0
	v_rcp_f32_e32 v143, v142
	s_nop 0
	v_fma_f32 v148, -v142, v143, 1.0
	v_fmac_f32_e32 v143, v148, v143
	v_div_scale_f32 v148, vcc, 1.0, v139, 1.0
	v_mul_f32_e32 v165, v148, v143
	v_fma_f32 v167, -v142, v165, v148
	v_fmac_f32_e32 v165, v167, v143
	v_fma_f32 v142, -v142, v165, v148
	v_div_fmas_f32 v142, v142, v143, v165
	v_div_fixup_f32 v139, v142, v139, 1.0
	v_div_scale_f32 v142, s[46:47], v138, v138, 1.0
	v_rcp_f32_e32 v143, v142
	s_nop 0
	v_fma_f32 v148, -v142, v143, 1.0
	v_fmac_f32_e32 v143, v148, v143
	v_div_scale_f32 v148, vcc, 1.0, v138, 1.0
	v_mul_f32_e32 v165, v148, v143
	v_fma_f32 v167, -v142, v165, v148
	v_fmac_f32_e32 v165, v167, v143
	v_fma_f32 v142, -v142, v165, v148
	v_div_fmas_f32 v142, v142, v143, v165
	v_div_fixup_f32 v138, v142, v138, 1.0
	v_pk_mul_f32 v[142:143], v[138:139], v[136:137]
	v_cvt_pk_bf16_f32 v136, v168, v169
	v_cvt_pk_bf16_f32 v137, v172, v173
	v_cvt_pk_bf16_f32 v138, v170, v171
	v_cvt_pk_bf16_f32 v139, v142, v143
	global_store_dwordx4 v[178:179], v[136:139], off offset:256
	s_and_b64 vcc, exec, s[44:45]
	s_nop 0
	v_lshl_add_u64 v[138:139], v[198:199], 2, v[196:197]
	global_load_dwordx4 v[168:171], v[138:139], off
	global_load_dwordx4 v[232:235], v[138:139], off offset:16
	s_waitcnt vmcnt(0)
	v_mov_b32_e32 v136, v169
	v_mov_b32_e32 v137, v170
	v_mov_b32_e32 v169, v171
	v_pk_add_f32 v[136:137], v[136:137], v[168:169]
	s_nop 0
	v_pk_add_f32 v[136:137], v[136:137], v[136:137] op_sel:[0,1] op_sel_hi:[1,0]
	s_cbranch_vccnz .LBB0_254
	v_mov_b64_e32 v[168:169], v[232:233]
	v_mov_b64_e32 v[170:171], v[234:235]
	s_mov_b32 s26, 0x3b000000
	v_mov_b32_e32 v138, v169
	v_mov_b32_e32 v139, v170
	v_mov_b32_e32 v169, v171
	v_pk_add_f32 v[138:139], v[138:139], v[168:169]
	s_nop 0
	v_add_f32_e32 v137, v138, v139
	v_add_f32_e32 v136, v136, v137
